# v21 + non-temporal hint on the EpiRes2 f32 residual-stream stores (P4/P8 epilogues): they are not re-read until ~1 GB of traffic later
# speedup vs baseline: 1.0047x; 1.0047x over previous
;     __device__ __forceinline__ void operator()(const f32x4 (&acc)[2][2][4][2], const Unit& u, int wr, int wc, int fr, int fq) const {
;     ...
;         const int urow = u.pm * BM + wr * 64, ucol = u.pn * BM + wc * 32;
;         const size_t ubase = (size_t)urow * ldc + ucol;
;         const char* bp = (const char*)(base + ubase); char* op = (char*)(out + ubase); char* zp = (char*)(zb + ubase);
;         const char* sp = (const char*)(bstats + 2 * (size_t)urow); float* osp = ostats + 2 * (size_t)urow;
;         const unsigned l4 = (unsigned)(fr * ldc + 8 * fq) * 4u, l2 = (unsigned)(fr * ldc + 8 * fq) * 2u, ls = (unsigned)fr * 8u;
;         const int col0 = ucol + 8 * fq;
;         f32x4 gv[2][2], cv[2][2];
; #pragma unroll
;         for (int bj = 0; bj < 2; ++bj)
; #pragma unroll
;             for (int n = 0; n < 2; ++n) { gv[bj][n] = *(const f32x4*)(bg + col0 + bj * HALF + 4 * n) * alpha;
;                 cv[bj][n] = *(const f32x4*)(bb + col0 + bj * HALF + 4 * n) * alpha + *(const f32x4*)(bias + col0 + bj * HALF + 4 * n); }
;         f32x2 sv_c = *(const f32x2*)(sp + ls);
;         f32x4 p0 = *(const f32x4*)(bp + l4), p1 = *(const f32x4*)(bp + l4 + 16);
; #pragma unroll
;         for (int g = 0; g < 8; ++g) { const int ai = g >> 2, m = g & 3; const int rr = ai * HALF + m * 16, rn = ((g + 1) >> 2) * HALF + ((g + 1) & 3) * 16;
;             f32x2 sv_n = sv_c; if (g + 1 < 8) sv_n = *(const f32x2*)(sp + (size_t)rn * 8 + ls);
;             float mu, r; stats_mr(sv_c, mu, r); float s1 = 0.f, s2 = 0.f;
; #pragma unroll
;             for (int bj = 0; bj < 2; ++bj) { const size_t ro = (size_t)rr * ldc + bj * HALF;
;                 f32x4 q0 = p0, q1 = p1;
;                 if (bj == 0) { q0 = *(const f32x4*)(bp + (ro + HALF) * 4 + l4); q1 = *(const f32x4*)(bp + (ro + HALF) * 4 + l4 + 16); }
;                 else if (g + 1 < 8) { q0 = *(const f32x4*)(bp + (size_t)rn * ldc * 4 + l4); q1 = *(const f32x4*)(bp + (size_t)rn * ldc * 4 + l4 + 16); }
;                 const f32x4 z0 = gv[bj][0] * ((p0 - mu) * r) + acc[ai][bj][m][0] + cv[bj][0], z1 = gv[bj][1] * ((p1 - mu) * r) + acc[ai][bj][m][1] + cv[bj][1];
;                 *(f32x4*)(op + ro * 4 + l4) = z0; *(f32x4*)(op + ro * 4 + l4 + 16) = z1;
;                 s1 += ((z0[0] + z0[1]) + (z0[2] + z0[3])) + ((z1[0] + z1[1]) + (z1[2] + z1[3]));
.LBB0_730:
	s_lshl_b32 s1, s83, 8
	s_add_i32 s24, s1, s93
	s_lshl_b32 s1, s82, 8
	s_or_b32 s1, s1, s94
	v_or_b32_e32 v130, s1, v1
	v_ashrrev_i32_e32 v131, 31, v130
	v_lshlrev_b64 v[130:131], 2, v[130:131]
	v_lshl_add_u64 v[160:161], s[48:49], 0, v[130:131]
	v_lshl_add_u64 v[168:169], s[50:51], 0, v[130:131]
	v_lshl_add_u64 v[202:203], s[44:45], 0, v[130:131]
	global_load_dwordx4 v[130:133], v[160:161], off offset:16
	global_load_dwordx4 v[134:137], v[160:161], off
	s_ashr_i32 s25, s24, 31
	s_ashr_i32 s4, s1, 31
	s_lshl_b64 s[34:35], s[24:25], 10
	s_add_u32 s34, s34, s1
	s_addc_u32 s35, s35, s4
	s_lshl_b64 s[60:61], s[34:35], 2
	s_add_u32 s70, s96, s60
	s_addc_u32 s71, s95, s61
	s_lshl_b64 s[24:25], s[24:25], 3
	v_lshl_add_u64 v[204:205], v[148:149], 0, s[24:25]
	s_mov_b64 s[4:5], 0x10000
	s_add_u32 s82, s46, s24
	s_addc_u32 s83, s47, s25
	s_waitcnt vmcnt(0)
	v_pk_mul_f32 v[194:195], v[132:133], s[26:27] op_sel_hi:[1,0]
	v_pk_mul_f32 v[162:163], v[136:137], s[26:27] op_sel_hi:[1,0]
	v_pk_mul_f32 v[170:171], v[134:135], s[26:27] op_sel_hi:[1,0]
	global_load_dwordx4 v[134:137], v[168:169], off offset:16
	global_load_dwordx4 v[164:167], v[168:169], off
	global_load_dwordx4 v[172:175], v[202:203], off offset:16
	global_load_dwordx4 v[176:179], v[202:203], off
	v_pk_mul_f32 v[196:197], v[130:131], s[26:27] op_sel_hi:[1,0]
	s_waitcnt vmcnt(1)
	v_pk_fma_f32 v[190:191], v[136:137], s[26:27], v[174:175] op_sel_hi:[1,0,1]
	v_pk_fma_f32 v[192:193], v[134:135], s[26:27], v[172:173] op_sel_hi:[1,0,1]
	global_load_dwordx4 v[130:133], v[160:161], off offset:528
	global_load_dwordx4 v[134:137], v[160:161], off offset:512
	s_waitcnt vmcnt(2)
	v_pk_fma_f32 v[186:187], v[166:167], s[26:27], v[178:179] op_sel_hi:[1,0,1]
	v_pk_fma_f32 v[188:189], v[164:165], s[26:27], v[176:177] op_sel_hi:[1,0,1]
	s_waitcnt vmcnt(1)
	v_pk_mul_f32 v[178:179], v[130:131], s[26:27] op_sel_hi:[1,0]
	s_waitcnt vmcnt(0)
	v_pk_mul_f32 v[160:161], v[136:137], s[26:27] op_sel_hi:[1,0]
	v_pk_mul_f32 v[164:165], v[134:135], s[26:27] op_sel_hi:[1,0]
	global_load_dwordx4 v[134:137], v[168:169], off offset:528
	s_nop 0
	global_load_dwordx4 v[166:169], v[168:169], off offset:512
	s_nop 0
	global_load_dwordx4 v[198:201], v[202:203], off offset:528
	global_load_dwordx4 v[172:175], v[202:203], off offset:512
	global_load_dwordx2 v[130:131], v[204:205], off
	v_lshl_add_u64 v[202:203], s[70:71], 0, v[150:151]
	global_load_dwordx4 v[212:215], v[202:203], off offset:16
	global_load_dwordx4 v[216:219], v[202:203], off
	global_load_dwordx2 v[206:207], v[204:205], off offset:128
	s_waitcnt vmcnt(4)
	v_pk_fma_f32 v[174:175], v[168:169], s[26:27], v[174:175] op_sel_hi:[1,0,1]
	s_waitcnt vmcnt(3)
	v_pk_mul_f32 v[210:211], v[130:131], s[54:55] op_sel_hi:[1,0]
	v_pk_fma_f32 v[176:177], v[166:167], s[26:27], v[172:173] op_sel_hi:[1,0,1]
	v_fma_f32 v130, -v210, v210, v211
	v_add_f32_e32 v130, 0x3727c5ac, v130
	v_pk_mul_f32 v[172:173], v[132:133], s[26:27] op_sel_hi:[1,0]
	v_pk_fma_f32 v[166:167], v[136:137], s[26:27], v[200:201] op_sel_hi:[1,0,1]
	v_pk_fma_f32 v[168:169], v[134:135], s[26:27], v[198:199] op_sel_hi:[1,0,1]
	v_rsq_f32_e32 v208, v130
	global_load_dwordx4 v[130:133], v[202:203], off offset:528
	global_load_dwordx4 v[134:137], v[202:203], off offset:512
	s_waitcnt vmcnt(3)
	v_sub_f32_e32 v217, v217, v210
	v_sub_f32_e32 v216, v216, v210
	v_sub_f32_e32 v219, v219, v210
	v_sub_f32_e32 v218, v218, v210
	v_pk_mul_f32 v[218:219], v[218:219], v[208:209] op_sel_hi:[1,0]
	v_pk_mul_f32 v[216:217], v[216:217], v[208:209] op_sel_hi:[1,0]
	v_sub_f32_e32 v213, v213, v210
	v_sub_f32_e32 v212, v212, v210
	v_sub_f32_e32 v215, v215, v210
	v_sub_f32_e32 v214, v214, v210
	v_pk_fma_f32 v[126:127], v[170:171], v[216:217], v[126:127]
	v_pk_fma_f32 v[128:129], v[162:163], v[218:219], v[128:129]
	v_pk_mul_f32 v[214:215], v[214:215], v[208:209] op_sel_hi:[1,0]
	v_pk_mul_f32 v[212:213], v[212:213], v[208:209] op_sel_hi:[1,0]
	v_pk_add_f32 v[128:129], v[186:187], v[128:129]
	v_pk_add_f32 v[126:127], v[188:189], v[126:127]
	v_pk_fma_f32 v[122:123], v[196:197], v[212:213], v[122:123]
	v_pk_fma_f32 v[124:125], v[194:195], v[214:215], v[124:125]
	v_pk_add_f32 v[122:123], v[192:193], v[122:123]
	v_pk_add_f32 v[124:125], v[190:191], v[124:125]
	v_add_f32_e32 v211, v126, v127
	v_add_f32_e32 v212, v128, v129
	v_add_f32_e32 v211, v211, v212
	v_add_f32_e32 v212, v122, v123
	v_add_f32_e32 v213, v124, v125
	v_add_f32_e32 v212, v212, v213
	v_add_f32_e32 v211, v211, v212
	v_add_f32_e32 v214, 0, v211
	v_mul_f32_e32 v211, v127, v127
	v_mul_f32_e32 v212, v129, v129
	v_fmac_f32_e32 v211, v126, v126
	v_fmac_f32_e32 v212, v128, v128
	v_add_f32_e32 v211, v211, v212
	v_mul_f32_e32 v212, v123, v123
	v_mul_f32_e32 v213, v125, v125
	v_lshl_add_u64 v[200:201], v[152:153], 0, s[60:61]
	v_fmac_f32_e32 v212, v122, v122
	v_fmac_f32_e32 v213, v124, v124
	global_store_dwordx4 v[200:201], v[126:129], off nt
	global_store_dwordx4 v[200:201], v[122:125], off offset:16 nt
	v_add_f32_e32 v212, v212, v213
	v_cvt_pk_bf16_f32 v126, v126, v127
	v_cvt_pk_bf16_f32 v127, v128, v129
	v_cvt_pk_bf16_f32 v128, v122, v123
	v_lshl_add_u64 v[198:199], s[34:35], 1, v[154:155]
	v_lshl_add_u64 v[122:123], v[202:203], 0, s[4:5]
	s_mov_b32 s4, 0x10000
	v_add_f32_e32 v211, v211, v212
	v_add_co_u32_e32 v212, vcc, s4, v202
	v_cvt_pk_bf16_f32 v129, v124, v125
	global_store_dwordx4 v[198:199], v[126:129], off
	s_nop 0
	v_addc_co_u32_e32 v213, vcc, 0, v203, vcc
	global_load_dwordx4 v[126:129], v[212:213], off
	s_nop 0
	global_load_dwordx4 v[122:125], v[122:123], off offset:16
	s_waitcnt vmcnt(6)
	v_sub_f32_e32 v131, v131, v210
	s_waitcnt vmcnt(5)
; __device__ __forceinline__ unsigned cvt_pk_bf16(float lo, float hi) { unsigned r; asm volatile("v_cvt_pk_bf16_f32 %0, %1, %2" : "=v"(r) : "v"(lo), "v"(hi)); return r; }
; __device__ __forceinline__ void stats_mr(const f32x2 s, float& mu, float& r) { mu = s.x * (1.0f / 1024.0f); const float var = s.y * (1.0f / 1024.0f) - mu * mu; r = __builtin_amdgcn_rsqf(var + 1e-5f); }
;     __device__ __forceinline__ void operator()(const f32x4 (&acc)[2][2][4][2], const Unit& u, int wr, int wc, int fr, int fq) const {
;     ...
;         for (int g = 0; g < 8; ++g) { const int ai = g >> 2, m = g & 3; const int rr = ai * HALF + m * 16, rn = ((g + 1) >> 2) * HALF + ((g + 1) & 3) * 16;
;             f32x2 sv_n = sv_c; if (g + 1 < 8) sv_n = *(const f32x2*)(sp + (size_t)rn * 8 + ls);
;             float mu, r; stats_mr(sv_c, mu, r); float s1 = 0.f, s2 = 0.f;
; #pragma unroll
;             for (int bj = 0; bj < 2; ++bj) { const size_t ro = (size_t)rr * ldc + bj * HALF;
;                 f32x4 q0 = p0, q1 = p1;
;                 if (bj == 0) { q0 = *(const f32x4*)(bp + (ro + HALF) * 4 + l4); q1 = *(const f32x4*)(bp + (ro + HALF) * 4 + l4 + 16); }
;                 else if (g + 1 < 8) { q0 = *(const f32x4*)(bp + (size_t)rn * ldc * 4 + l4); q1 = *(const f32x4*)(bp + (size_t)rn * ldc * 4 + l4 + 16); }
;                 const f32x4 z0 = gv[bj][0] * ((p0 - mu) * r) + acc[ai][bj][m][0] + cv[bj][0], z1 = gv[bj][1] * ((p1 - mu) * r) + acc[ai][bj][m][1] + cv[bj][1];
;                 *(f32x4*)(op + ro * 4 + l4) = z0; *(f32x4*)(op + ro * 4 + l4 + 16) = z1;
;                 s1 += ((z0[0] + z0[1]) + (z0[2] + z0[3])) + ((z1[0] + z1[1]) + (z1[2] + z1[3]));
;                 s2 += ((z0[0] * z0[0] + z0[1] * z0[1]) + (z0[2] * z0[2] + z0[3] * z0[3])) + ((z1[0] * z1[0] + z1[1] * z1[1]) + (z1[2] * z1[2] + z1[3] * z1[3]));
;                 if (zb) { u32x4 w; w.x = cvt_pk_bf16(z0[0], z0[1]); w.y = cvt_pk_bf16(z0[2], z0[3]); w.z = cvt_pk_bf16(z1[0], z1[1]); w.w = cvt_pk_bf16(z1[2], z1[3]); *(u32x4*)(zp + ro * 2 + l2) = w; }
;                 p0 = q0; p1 = q1; }
;             s1 += __shfl_xor(s1, 16); s2 += __shfl_xor(s2, 16); s1 += __shfl_xor(s1, 32); s2 += __shfl_xor(s2, 32);
;             if (fq == 0) { atomicAdd(osp + 2 * (rr + fr), s1); atomicAdd(osp + 2 * (rr + fr) + 1, s2); }
;             sv_c = sv_n; }
	v_sub_f32_e32 v135, v135, v210
	v_sub_f32_e32 v134, v134, v210
	v_sub_f32_e32 v137, v137, v210
	v_sub_f32_e32 v136, v136, v210
	v_pk_mul_f32 v[136:137], v[136:137], v[208:209] op_sel_hi:[1,0]
	v_pk_mul_f32 v[134:135], v[134:135], v[208:209] op_sel_hi:[1,0]
	v_sub_f32_e32 v130, v130, v210
	v_sub_f32_e32 v133, v133, v210
	v_sub_f32_e32 v132, v132, v210
	v_pk_fma_f32 v[118:119], v[164:165], v[134:135], v[118:119]
	v_pk_fma_f32 v[120:121], v[160:161], v[136:137], v[120:121]
	v_pk_mul_f32 v[132:133], v[132:133], v[208:209] op_sel_hi:[1,0]
	v_pk_mul_f32 v[130:131], v[130:131], v[208:209] op_sel_hi:[1,0]
	v_pk_add_f32 v[120:121], v[174:175], v[120:121]
	v_pk_add_f32 v[118:119], v[176:177], v[118:119]
	v_pk_fma_f32 v[114:115], v[178:179], v[130:131], v[114:115]
	v_pk_fma_f32 v[116:117], v[172:173], v[132:133], v[116:117]
	v_pk_add_f32 v[114:115], v[168:169], v[114:115]
	v_pk_add_f32 v[116:117], v[166:167], v[116:117]
	v_add_f32_e32 v130, v118, v119
	v_add_f32_e32 v131, v120, v121
	v_add_f32_e32 v130, v130, v131
	v_add_f32_e32 v131, v114, v115
	v_add_f32_e32 v132, v116, v117
	v_add_f32_e32 v131, v131, v132
	v_add_f32_e32 v130, v130, v131
	v_mul_f32_e32 v131, v119, v119
	v_mul_f32_e32 v132, v121, v121
	v_fmac_f32_e32 v131, v118, v118
	v_fmac_f32_e32 v132, v120, v120
	global_store_dwordx4 v[200:201], v[118:121], off offset:512 nt
	global_store_dwordx4 v[200:201], v[114:117], off offset:528 nt
	v_add_f32_e32 v131, v131, v132
	v_mul_f32_e32 v132, v115, v115
	v_mul_f32_e32 v133, v117, v117
	v_cvt_pk_bf16_f32 v118, v118, v119
	v_cvt_pk_bf16_f32 v119, v120, v121
	v_cvt_pk_bf16_f32 v120, v114, v115
	v_and_b32_e32 v115, 64, v224
	v_fmac_f32_e32 v132, v114, v114
	v_fmac_f32_e32 v133, v116, v116
	v_cvt_pk_bf16_f32 v121, v116, v117
	v_xor_b32_e32 v114, 16, v224
	v_add_u32_e32 v116, 64, v115
	v_add_f32_e32 v132, v132, v133
	v_cmp_lt_i32_e32 vcc, v114, v116
	v_add_f32_e32 v131, v131, v132
	v_add_f32_e32 v130, v130, v214
	v_cndmask_b32_e32 v114, v224, v114, vcc
	v_add_f32_e32 v131, v211, v131
	v_lshlrev_b32_e32 v133, 2, v114
	ds_bpermute_b32 v114, v133, v130
	ds_bpermute_b32 v115, v133, v131
	v_xor_b32_e32 v117, 32, v224
	v_cmp_lt_i32_e32 vcc, v117, v116
	v_lshlrev_b32_e32 v137, 2, v146
	s_waitcnt lgkmcnt(1)
	v_add_f32_e32 v114, v130, v114
	v_cndmask_b32_e32 v116, v224, v117, vcc
	s_waitcnt lgkmcnt(0)
	v_add_f32_e32 v115, v131, v115
	v_lshlrev_b32_e32 v136, 2, v116
	ds_bpermute_b32 v116, v136, v114
	ds_bpermute_b32 v117, v136, v115
	global_store_dwordx4 v[198:199], v[118:121], off offset:256
	s_and_saveexec_b64 s[24:25], s[40:41]
	s_mov_b32 s5, 0x90000
	s_cbranch_execz .LBB0_732
	s_waitcnt lgkmcnt(1)
	v_add_f32_e32 v114, v114, v116
	s_waitcnt lgkmcnt(0)
	v_add_f32_e32 v115, v115, v117
	global_atomic_add_f32 v137, v114, s[82:83]
	global_atomic_add_f32 v137, v115, s[82:83] offset:4
.LBB0_732:
	s_or_b64 exec, exec, s[24:25]
	v_pk_mul_f32 v[134:135], v[206:207], s[54:55] op_sel_hi:[1,0]
	s_mov_b64 s[24:25], 0x10200
	v_fma_f32 v114, -v134, v134, v135
	v_add_f32_e32 v114, 0x3727c5ac, v114
	v_rsq_f32_e32 v132, v114
	v_lshl_add_u64 v[114:115], v[202:203], 0, s[24:25]
	global_load_dwordx2 v[130:131], v[204:205], off offset:256
	global_load_dwordx4 v[118:121], v[212:213], off offset:512
	s_waitcnt lgkmcnt(0)
	global_load_dwordx4 v[114:117], v[114:115], off offset:16
	s_waitcnt vmcnt(7)
	v_sub_f32_e32 v127, v127, v134
	v_sub_f32_e32 v126, v126, v134
	v_sub_f32_e32 v129, v129, v134
	v_sub_f32_e32 v128, v128, v134
	v_pk_mul_f32 v[128:129], v[132:133], v[128:129] op_sel_hi:[0,1]
	v_pk_mul_f32 v[126:127], v[132:133], v[126:127] op_sel_hi:[0,1]
	s_waitcnt vmcnt(6)
	v_sub_f32_e32 v123, v123, v134
	v_sub_f32_e32 v122, v122, v134
	v_sub_f32_e32 v125, v125, v134
	v_sub_f32_e32 v124, v124, v134
	v_pk_fma_f32 v[110:111], v[170:171], v[126:127], v[110:111]
	v_pk_fma_f32 v[112:113], v[162:163], v[128:129], v[112:113]
	v_pk_mul_f32 v[124:125], v[132:133], v[124:125] op_sel_hi:[0,1]
	v_pk_mul_f32 v[122:123], v[132:133], v[122:123] op_sel_hi:[0,1]
	v_pk_add_f32 v[112:113], v[186:187], v[112:113]
	v_pk_add_f32 v[110:111], v[188:189], v[110:111]
	v_pk_fma_f32 v[106:107], v[196:197], v[122:123], v[106:107]
	v_pk_fma_f32 v[108:109], v[194:195], v[124:125], v[108:109]
	v_pk_add_f32 v[106:107], v[192:193], v[106:107]
	v_pk_add_f32 v[108:109], v[190:191], v[108:109]
	v_add_f32_e32 v122, v110, v111
	v_add_f32_e32 v123, v112, v113
	v_add_f32_e32 v122, v122, v123
	v_add_f32_e32 v123, v106, v107
	v_add_f32_e32 v126, v108, v109
	v_add_f32_e32 v123, v123, v126
	v_add_f32_e32 v122, v122, v123
	v_add_f32_e32 v128, 0, v122
	v_mul_f32_e32 v122, v111, v111
	v_mul_f32_e32 v123, v113, v113
	v_fmac_f32_e32 v122, v110, v110
	v_fmac_f32_e32 v123, v112, v112
	v_add_co_u32_e32 v124, vcc, s4, v200
	v_add_f32_e32 v122, v122, v123
	v_mul_f32_e32 v123, v107, v107
	v_mul_f32_e32 v126, v109, v109
	v_addc_co_u32_e32 v125, vcc, 0, v201, vcc
	v_fmac_f32_e32 v123, v106, v106
	v_fmac_f32_e32 v126, v108, v108
	s_mov_b32 s1, 0x8000
	v_add_f32_e32 v123, v123, v126
	v_add_co_u32_e32 v126, vcc, s1, v198
	s_mov_b32 s1, 0x20000
	s_nop 0
	v_addc_co_u32_e32 v127, vcc, 0, v199, vcc
	v_add_f32_e32 v129, v122, v123
	s_mov_b64 s[24:25], 0x20000
	v_add_co_u32_e32 v122, vcc, s1, v202
	global_store_dwordx4 v[124:125], v[110:113], off nt
	global_store_dwordx4 v[124:125], v[106:109], off offset:16 nt
	v_addc_co_u32_e32 v123, vcc, 0, v203, vcc
	v_cvt_pk_bf16_f32 v110, v110, v111
	v_cvt_pk_bf16_f32 v111, v112, v113
	v_cvt_pk_bf16_f32 v112, v106, v107
	v_cvt_pk_bf16_f32 v113, v108, v109
	global_store_dwordx4 v[126:127], v[110:113], off
	v_lshl_add_u64 v[106:107], v[202:203], 0, s[24:25]
	global_load_dwordx4 v[110:113], v[122:123], off
	s_nop 0
	global_load_dwordx4 v[106:109], v[106:107], off offset:16
	s_waitcnt vmcnt(6)
; __device__ __forceinline__ unsigned cvt_pk_bf16(float lo, float hi) { unsigned r; asm volatile("v_cvt_pk_bf16_f32 %0, %1, %2" : "=v"(r) : "v"(lo), "v"(hi)); return r; }
; __device__ __forceinline__ void stats_mr(const f32x2 s, float& mu, float& r) { mu = s.x * (1.0f / 1024.0f); const float var = s.y * (1.0f / 1024.0f) - mu * mu; r = __builtin_amdgcn_rsqf(var + 1e-5f); }
;     __device__ __forceinline__ void operator()(const f32x4 (&acc)[2][2][4][2], const Unit& u, int wr, int wc, int fr, int fq) const {
;     ...
;         for (int g = 0; g < 8; ++g) { const int ai = g >> 2, m = g & 3; const int rr = ai * HALF + m * 16, rn = ((g + 1) >> 2) * HALF + ((g + 1) & 3) * 16;
;             f32x2 sv_n = sv_c; if (g + 1 < 8) sv_n = *(const f32x2*)(sp + (size_t)rn * 8 + ls);
;             float mu, r; stats_mr(sv_c, mu, r); float s1 = 0.f, s2 = 0.f;
; #pragma unroll
;             for (int bj = 0; bj < 2; ++bj) { const size_t ro = (size_t)rr * ldc + bj * HALF;
;                 f32x4 q0 = p0, q1 = p1;
;                 if (bj == 0) { q0 = *(const f32x4*)(bp + (ro + HALF) * 4 + l4); q1 = *(const f32x4*)(bp + (ro + HALF) * 4 + l4 + 16); }
;                 else if (g + 1 < 8) { q0 = *(const f32x4*)(bp + (size_t)rn * ldc * 4 + l4); q1 = *(const f32x4*)(bp + (size_t)rn * ldc * 4 + l4 + 16); }
;                 const f32x4 z0 = gv[bj][0] * ((p0 - mu) * r) + acc[ai][bj][m][0] + cv[bj][0], z1 = gv[bj][1] * ((p1 - mu) * r) + acc[ai][bj][m][1] + cv[bj][1];
;                 *(f32x4*)(op + ro * 4 + l4) = z0; *(f32x4*)(op + ro * 4 + l4 + 16) = z1;
;                 s1 += ((z0[0] + z0[1]) + (z0[2] + z0[3])) + ((z1[0] + z1[1]) + (z1[2] + z1[3]));
;                 s2 += ((z0[0] * z0[0] + z0[1] * z0[1]) + (z0[2] * z0[2] + z0[3] * z0[3])) + ((z1[0] * z1[0] + z1[1] * z1[1]) + (z1[2] * z1[2] + z1[3] * z1[3]));
;                 if (zb) { u32x4 w; w.x = cvt_pk_bf16(z0[0], z0[1]); w.y = cvt_pk_bf16(z0[2], z0[3]); w.z = cvt_pk_bf16(z1[0], z1[1]); w.w = cvt_pk_bf16(z1[2], z1[3]); *(u32x4*)(zp + ro * 2 + l2) = w; }
;                 p0 = q0; p1 = q1; }
;             s1 += __shfl_xor(s1, 16); s2 += __shfl_xor(s2, 16); s1 += __shfl_xor(s1, 32); s2 += __shfl_xor(s2, 32);
;             if (fq == 0) { atomicAdd(osp + 2 * (rr + fr), s1); atomicAdd(osp + 2 * (rr + fr) + 1, s2); }
;             sv_c = sv_n; }
	v_sub_f32_e32 v119, v119, v134
	v_sub_f32_e32 v118, v118, v134
	v_sub_f32_e32 v121, v121, v134
	v_sub_f32_e32 v120, v120, v134
	v_pk_mul_f32 v[120:121], v[132:133], v[120:121] op_sel_hi:[0,1]
	v_pk_mul_f32 v[118:119], v[132:133], v[118:119] op_sel_hi:[0,1]
	s_waitcnt vmcnt(5)
	v_sub_f32_e32 v115, v115, v134
	v_sub_f32_e32 v114, v114, v134
	v_sub_f32_e32 v117, v117, v134
	v_sub_f32_e32 v116, v116, v134
	v_pk_fma_f32 v[102:103], v[164:165], v[118:119], v[102:103]
	v_pk_fma_f32 v[104:105], v[160:161], v[120:121], v[104:105]
	v_pk_mul_f32 v[116:117], v[132:133], v[116:117] op_sel_hi:[0,1]
	v_pk_mul_f32 v[114:115], v[132:133], v[114:115] op_sel_hi:[0,1]
	v_pk_add_f32 v[104:105], v[174:175], v[104:105]
	v_pk_add_f32 v[102:103], v[176:177], v[102:103]
	v_pk_fma_f32 v[98:99], v[178:179], v[114:115], v[98:99]
	v_pk_fma_f32 v[100:101], v[172:173], v[116:117], v[100:101]
	v_pk_add_f32 v[98:99], v[168:169], v[98:99]
	v_pk_add_f32 v[100:101], v[166:167], v[100:101]
	v_add_f32_e32 v114, v102, v103
	v_add_f32_e32 v115, v104, v105
	v_add_f32_e32 v114, v114, v115
	v_add_f32_e32 v115, v98, v99
	v_add_f32_e32 v116, v100, v101
	v_add_f32_e32 v115, v115, v116
	v_add_f32_e32 v114, v114, v115
	v_mul_f32_e32 v115, v103, v103
	v_mul_f32_e32 v116, v105, v105
	v_fmac_f32_e32 v115, v102, v102
	v_fmac_f32_e32 v116, v104, v104
	v_add_f32_e32 v115, v115, v116
	v_mul_f32_e32 v116, v99, v99
	v_mul_f32_e32 v117, v101, v101
	v_fmac_f32_e32 v116, v98, v98
	v_fmac_f32_e32 v117, v100, v100
	v_add_f32_e32 v116, v116, v117
	v_add_f32_e32 v115, v115, v116
	v_add_f32_e32 v114, v128, v114
	v_add_f32_e32 v115, v129, v115
	global_store_dwordx4 v[124:125], v[102:105], off offset:512 nt
	global_store_dwordx4 v[124:125], v[98:101], off offset:528 nt
	s_nop 0
	v_cvt_pk_bf16_f32 v102, v102, v103
	v_cvt_pk_bf16_f32 v103, v104, v105
	v_cvt_pk_bf16_f32 v104, v98, v99
	ds_bpermute_b32 v98, v133, v114
	ds_bpermute_b32 v99, v133, v115
	v_cvt_pk_bf16_f32 v105, v100, v101
	global_store_dwordx4 v[126:127], v[102:105], off offset:256
	s_waitcnt lgkmcnt(1)
	v_add_f32_e32 v98, v114, v98
	s_waitcnt lgkmcnt(0)
	v_add_f32_e32 v99, v115, v99
	ds_bpermute_b32 v100, v136, v98
	ds_bpermute_b32 v101, v136, v99
	s_and_saveexec_b64 s[24:25], s[40:41]
	s_cbranch_execz .LBB0_734
	s_waitcnt lgkmcnt(1)
	v_add_f32_e32 v98, v98, v100
	s_waitcnt lgkmcnt(0)
	v_add_f32_e32 v99, v99, v101
	global_atomic_add_f32 v137, v98, s[82:83] offset:128
	global_atomic_add_f32 v137, v99, s[82:83] offset:132
.LBB0_734:
	s_or_b64 exec, exec, s[24:25]
	v_pk_mul_f32 v[118:119], v[130:131], s[54:55] op_sel_hi:[1,0]
	s_mov_b64 s[24:25], 0x20200
	v_fma_f32 v98, -v118, v118, v119
	v_add_f32_e32 v98, 0x3727c5ac, v98
	v_rsq_f32_e32 v116, v98
	v_lshl_add_u64 v[98:99], v[202:203], 0, s[24:25]
	global_load_dwordx2 v[114:115], v[204:205], off offset:384
	global_load_dwordx4 v[102:105], v[122:123], off offset:512
	s_waitcnt lgkmcnt(0)
	global_load_dwordx4 v[98:101], v[98:99], off offset:16
	s_waitcnt vmcnt(7)
	v_sub_f32_e32 v111, v111, v118
	v_sub_f32_e32 v110, v110, v118
	v_sub_f32_e32 v113, v113, v118
	v_sub_f32_e32 v112, v112, v118
	v_pk_mul_f32 v[112:113], v[116:117], v[112:113] op_sel_hi:[0,1]
	v_pk_mul_f32 v[110:111], v[116:117], v[110:111] op_sel_hi:[0,1]
	s_waitcnt vmcnt(6)
	v_sub_f32_e32 v107, v107, v118
	v_sub_f32_e32 v106, v106, v118
	v_sub_f32_e32 v109, v109, v118
	v_sub_f32_e32 v108, v108, v118
	v_pk_fma_f32 v[94:95], v[170:171], v[110:111], v[94:95]
	v_pk_fma_f32 v[96:97], v[162:163], v[112:113], v[96:97]
	v_pk_mul_f32 v[108:109], v[116:117], v[108:109] op_sel_hi:[0,1]
	v_pk_mul_f32 v[106:107], v[116:117], v[106:107] op_sel_hi:[0,1]
	v_pk_add_f32 v[96:97], v[186:187], v[96:97]
	v_pk_add_f32 v[94:95], v[188:189], v[94:95]
	v_pk_fma_f32 v[90:91], v[196:197], v[106:107], v[90:91]
	v_pk_fma_f32 v[92:93], v[194:195], v[108:109], v[92:93]
	v_pk_add_f32 v[90:91], v[192:193], v[90:91]
	v_pk_add_f32 v[92:93], v[190:191], v[92:93]
	v_add_f32_e32 v106, v94, v95
	v_add_f32_e32 v107, v96, v97
	v_add_f32_e32 v106, v106, v107
	v_add_f32_e32 v107, v90, v91
	v_add_f32_e32 v110, v92, v93
	v_add_f32_e32 v107, v107, v110
	v_add_f32_e32 v106, v106, v107
	v_add_f32_e32 v112, 0, v106
	v_mul_f32_e32 v106, v95, v95
	v_mul_f32_e32 v107, v97, v97
	v_fmac_f32_e32 v106, v94, v94
	v_fmac_f32_e32 v107, v96, v96
	v_add_co_u32_e32 v108, vcc, s1, v200
	v_add_f32_e32 v106, v106, v107
	v_mul_f32_e32 v107, v91, v91
	v_mul_f32_e32 v110, v93, v93
	v_addc_co_u32_e32 v109, vcc, 0, v201, vcc
	v_fmac_f32_e32 v107, v90, v90
	v_fmac_f32_e32 v110, v92, v92
	v_add_f32_e32 v107, v107, v110
	v_add_co_u32_e32 v110, vcc, s4, v198
	s_mov_b32 s1, 0x30000
	s_nop 0
	v_addc_co_u32_e32 v111, vcc, 0, v199, vcc
	v_add_f32_e32 v113, v106, v107
	s_mov_b64 s[24:25], 0x30000
	v_add_co_u32_e32 v106, vcc, s1, v202
	global_store_dwordx4 v[108:109], v[94:97], off nt
	global_store_dwordx4 v[108:109], v[90:93], off offset:16 nt
	v_addc_co_u32_e32 v107, vcc, 0, v203, vcc
	v_cvt_pk_bf16_f32 v94, v94, v95
	v_cvt_pk_bf16_f32 v95, v96, v97
	v_cvt_pk_bf16_f32 v96, v90, v91
	v_cvt_pk_bf16_f32 v97, v92, v93
	global_store_dwordx4 v[110:111], v[94:97], off
	v_lshl_add_u64 v[90:91], v[202:203], 0, s[24:25]
	global_load_dwordx4 v[94:97], v[106:107], off
	s_nop 0
	global_load_dwordx4 v[90:93], v[90:91], off offset:16
	s_waitcnt vmcnt(6)
	v_sub_f32_e32 v103, v103, v118
	v_sub_f32_e32 v102, v102, v118
	v_sub_f32_e32 v105, v105, v118
	v_sub_f32_e32 v104, v104, v118
	v_pk_mul_f32 v[104:105], v[116:117], v[104:105] op_sel_hi:[0,1]
	v_pk_mul_f32 v[102:103], v[116:117], v[102:103] op_sel_hi:[0,1]
	s_waitcnt vmcnt(5)
; __device__ __forceinline__ unsigned cvt_pk_bf16(float lo, float hi) { unsigned r; asm volatile("v_cvt_pk_bf16_f32 %0, %1, %2" : "=v"(r) : "v"(lo), "v"(hi)); return r; }
; __device__ __forceinline__ void stats_mr(const f32x2 s, float& mu, float& r) { mu = s.x * (1.0f / 1024.0f); const float var = s.y * (1.0f / 1024.0f) - mu * mu; r = __builtin_amdgcn_rsqf(var + 1e-5f); }
;     __device__ __forceinline__ void operator()(const f32x4 (&acc)[2][2][4][2], const Unit& u, int wr, int wc, int fr, int fq) const {
;     ...
;         for (int g = 0; g < 8; ++g) { const int ai = g >> 2, m = g & 3; const int rr = ai * HALF + m * 16, rn = ((g + 1) >> 2) * HALF + ((g + 1) & 3) * 16;
;             f32x2 sv_n = sv_c; if (g + 1 < 8) sv_n = *(const f32x2*)(sp + (size_t)rn * 8 + ls);
;             float mu, r; stats_mr(sv_c, mu, r); float s1 = 0.f, s2 = 0.f;
; #pragma unroll
;             for (int bj = 0; bj < 2; ++bj) { const size_t ro = (size_t)rr * ldc + bj * HALF;
;                 f32x4 q0 = p0, q1 = p1;
;                 if (bj == 0) { q0 = *(const f32x4*)(bp + (ro + HALF) * 4 + l4); q1 = *(const f32x4*)(bp + (ro + HALF) * 4 + l4 + 16); }
;                 else if (g + 1 < 8) { q0 = *(const f32x4*)(bp + (size_t)rn * ldc * 4 + l4); q1 = *(const f32x4*)(bp + (size_t)rn * ldc * 4 + l4 + 16); }
;                 const f32x4 z0 = gv[bj][0] * ((p0 - mu) * r) + acc[ai][bj][m][0] + cv[bj][0], z1 = gv[bj][1] * ((p1 - mu) * r) + acc[ai][bj][m][1] + cv[bj][1];
;                 *(f32x4*)(op + ro * 4 + l4) = z0; *(f32x4*)(op + ro * 4 + l4 + 16) = z1;
;                 s1 += ((z0[0] + z0[1]) + (z0[2] + z0[3])) + ((z1[0] + z1[1]) + (z1[2] + z1[3]));
;                 s2 += ((z0[0] * z0[0] + z0[1] * z0[1]) + (z0[2] * z0[2] + z0[3] * z0[3])) + ((z1[0] * z1[0] + z1[1] * z1[1]) + (z1[2] * z1[2] + z1[3] * z1[3]));
;                 if (zb) { u32x4 w; w.x = cvt_pk_bf16(z0[0], z0[1]); w.y = cvt_pk_bf16(z0[2], z0[3]); w.z = cvt_pk_bf16(z1[0], z1[1]); w.w = cvt_pk_bf16(z1[2], z1[3]); *(u32x4*)(zp + ro * 2 + l2) = w; }
;                 p0 = q0; p1 = q1; }
;             s1 += __shfl_xor(s1, 16); s2 += __shfl_xor(s2, 16); s1 += __shfl_xor(s1, 32); s2 += __shfl_xor(s2, 32);
;             if (fq == 0) { atomicAdd(osp + 2 * (rr + fr), s1); atomicAdd(osp + 2 * (rr + fr) + 1, s2); }
;             sv_c = sv_n; }
	v_sub_f32_e32 v99, v99, v118
	v_sub_f32_e32 v98, v98, v118
	v_sub_f32_e32 v101, v101, v118
	v_sub_f32_e32 v100, v100, v118
	v_pk_fma_f32 v[86:87], v[164:165], v[102:103], v[86:87]
	v_pk_fma_f32 v[88:89], v[160:161], v[104:105], v[88:89]
	v_pk_mul_f32 v[100:101], v[116:117], v[100:101] op_sel_hi:[0,1]
	v_pk_mul_f32 v[98:99], v[116:117], v[98:99] op_sel_hi:[0,1]
	v_pk_add_f32 v[88:89], v[174:175], v[88:89]
	v_pk_add_f32 v[86:87], v[176:177], v[86:87]
	v_pk_fma_f32 v[82:83], v[178:179], v[98:99], v[82:83]
	v_pk_fma_f32 v[84:85], v[172:173], v[100:101], v[84:85]
	v_pk_add_f32 v[82:83], v[168:169], v[82:83]
	v_pk_add_f32 v[84:85], v[166:167], v[84:85]
	v_add_f32_e32 v98, v86, v87
	v_add_f32_e32 v99, v88, v89
	v_add_f32_e32 v98, v98, v99
	v_add_f32_e32 v99, v82, v83
	v_add_f32_e32 v100, v84, v85
	v_add_f32_e32 v99, v99, v100
	v_add_f32_e32 v98, v98, v99
	v_mul_f32_e32 v99, v87, v87
	v_mul_f32_e32 v100, v89, v89
	v_fmac_f32_e32 v99, v86, v86
	v_fmac_f32_e32 v100, v88, v88
	v_add_f32_e32 v99, v99, v100
	v_mul_f32_e32 v100, v83, v83
	v_mul_f32_e32 v101, v85, v85
	v_fmac_f32_e32 v100, v82, v82
	v_fmac_f32_e32 v101, v84, v84
	v_add_f32_e32 v100, v100, v101
	v_add_f32_e32 v99, v99, v100
	v_add_f32_e32 v98, v112, v98
	v_add_f32_e32 v99, v113, v99
	global_store_dwordx4 v[108:109], v[86:89], off offset:512 nt
	global_store_dwordx4 v[108:109], v[82:85], off offset:528 nt
	s_nop 0
	v_cvt_pk_bf16_f32 v86, v86, v87
	v_cvt_pk_bf16_f32 v87, v88, v89
	v_cvt_pk_bf16_f32 v88, v82, v83
	ds_bpermute_b32 v82, v133, v98
	ds_bpermute_b32 v83, v133, v99
	v_cvt_pk_bf16_f32 v89, v84, v85
	global_store_dwordx4 v[110:111], v[86:89], off offset:256
	s_waitcnt lgkmcnt(1)
	v_add_f32_e32 v82, v98, v82
	s_waitcnt lgkmcnt(0)
	v_add_f32_e32 v83, v99, v83
	ds_bpermute_b32 v84, v136, v82
	ds_bpermute_b32 v85, v136, v83
	s_and_saveexec_b64 s[24:25], s[40:41]
	s_cbranch_execz .LBB0_736
	s_waitcnt lgkmcnt(1)
	v_add_f32_e32 v82, v82, v84
	s_waitcnt lgkmcnt(0)
	v_add_f32_e32 v83, v83, v85
	global_atomic_add_f32 v137, v82, s[82:83] offset:256
	global_atomic_add_f32 v137, v83, s[82:83] offset:260
.LBB0_736:
	s_or_b64 exec, exec, s[24:25]
	v_pk_mul_f32 v[102:103], v[114:115], s[54:55] op_sel_hi:[1,0]
	s_mov_b64 s[24:25], 0x30200
	v_fma_f32 v82, -v102, v102, v103
	v_add_f32_e32 v82, 0x3727c5ac, v82
	v_rsq_f32_e32 v100, v82
	v_lshl_add_u64 v[82:83], v[202:203], 0, s[24:25]
	global_load_dwordx2 v[98:99], v[204:205], off offset:1024
	global_load_dwordx4 v[86:89], v[106:107], off offset:512
	s_waitcnt lgkmcnt(0)
	global_load_dwordx4 v[82:85], v[82:83], off offset:16
	s_waitcnt vmcnt(7)
	v_sub_f32_e32 v95, v95, v102
	v_sub_f32_e32 v94, v94, v102
	v_sub_f32_e32 v97, v97, v102
	v_sub_f32_e32 v96, v96, v102
	v_pk_mul_f32 v[96:97], v[100:101], v[96:97] op_sel_hi:[0,1]
	v_pk_mul_f32 v[94:95], v[100:101], v[94:95] op_sel_hi:[0,1]
	s_waitcnt vmcnt(6)
	v_sub_f32_e32 v91, v91, v102
	v_sub_f32_e32 v90, v90, v102
	v_sub_f32_e32 v93, v93, v102
	v_sub_f32_e32 v92, v92, v102
	v_pk_fma_f32 v[78:79], v[170:171], v[94:95], v[78:79]
	v_pk_fma_f32 v[80:81], v[162:163], v[96:97], v[80:81]
	v_pk_mul_f32 v[92:93], v[100:101], v[92:93] op_sel_hi:[0,1]
	v_pk_mul_f32 v[90:91], v[100:101], v[90:91] op_sel_hi:[0,1]
	v_pk_add_f32 v[80:81], v[186:187], v[80:81]
	v_pk_add_f32 v[78:79], v[188:189], v[78:79]
	v_pk_fma_f32 v[74:75], v[196:197], v[90:91], v[74:75]
	v_pk_fma_f32 v[76:77], v[194:195], v[92:93], v[76:77]
	v_pk_add_f32 v[74:75], v[192:193], v[74:75]
	v_pk_add_f32 v[76:77], v[190:191], v[76:77]
	v_add_f32_e32 v90, v78, v79
	v_add_f32_e32 v91, v80, v81
	v_add_f32_e32 v90, v90, v91
	v_add_f32_e32 v91, v74, v75
	v_add_f32_e32 v94, v76, v77
	v_add_f32_e32 v91, v91, v94
	v_add_f32_e32 v90, v90, v91
	v_add_f32_e32 v96, 0, v90
	v_mul_f32_e32 v90, v79, v79
	v_mul_f32_e32 v91, v81, v81
	v_fmac_f32_e32 v90, v78, v78
	v_fmac_f32_e32 v91, v80, v80
	v_add_co_u32_e32 v92, vcc, s1, v200
	v_add_f32_e32 v90, v90, v91
	v_mul_f32_e32 v91, v75, v75
	v_mul_f32_e32 v94, v77, v77
	v_addc_co_u32_e32 v93, vcc, 0, v201, vcc
	v_fmac_f32_e32 v91, v74, v74
	v_fmac_f32_e32 v94, v76, v76
	s_mov_b32 s1, 0x18000
	v_add_f32_e32 v91, v91, v94
	v_add_co_u32_e32 v94, vcc, s1, v198
	s_mov_b32 s1, 0x80000
	s_nop 0
	v_addc_co_u32_e32 v95, vcc, 0, v199, vcc
	v_add_f32_e32 v97, v90, v91
	s_mov_b64 s[24:25], 0x80000
	v_add_co_u32_e32 v90, vcc, s1, v202
	global_store_dwordx4 v[92:93], v[78:81], off nt
	global_store_dwordx4 v[92:93], v[74:77], off offset:16 nt
	v_addc_co_u32_e32 v91, vcc, 0, v203, vcc
	v_cvt_pk_bf16_f32 v78, v78, v79
	v_cvt_pk_bf16_f32 v79, v80, v81
	v_cvt_pk_bf16_f32 v80, v74, v75
	v_cvt_pk_bf16_f32 v81, v76, v77
	global_store_dwordx4 v[94:95], v[78:81], off
	v_lshl_add_u64 v[74:75], v[202:203], 0, s[24:25]
	global_load_dwordx4 v[78:81], v[90:91], off
	s_nop 0
	global_load_dwordx4 v[74:77], v[74:75], off offset:16
	s_waitcnt vmcnt(6)
	v_sub_f32_e32 v87, v87, v102
	v_sub_f32_e32 v86, v86, v102
	v_sub_f32_e32 v89, v89, v102
	v_sub_f32_e32 v88, v88, v102
	v_pk_mul_f32 v[88:89], v[100:101], v[88:89] op_sel_hi:[0,1]
	v_pk_mul_f32 v[86:87], v[100:101], v[86:87] op_sel_hi:[0,1]
	s_waitcnt vmcnt(5)
	v_sub_f32_e32 v83, v83, v102
	v_sub_f32_e32 v82, v82, v102
	v_sub_f32_e32 v85, v85, v102
	v_sub_f32_e32 v84, v84, v102
	v_pk_fma_f32 v[70:71], v[164:165], v[86:87], v[70:71]
	v_pk_fma_f32 v[72:73], v[160:161], v[88:89], v[72:73]
	v_pk_mul_f32 v[84:85], v[100:101], v[84:85] op_sel_hi:[0,1]
	v_pk_mul_f32 v[82:83], v[100:101], v[82:83] op_sel_hi:[0,1]
	v_pk_add_f32 v[72:73], v[174:175], v[72:73]
	v_pk_add_f32 v[70:71], v[176:177], v[70:71]
	v_pk_fma_f32 v[66:67], v[178:179], v[82:83], v[66:67]
	v_pk_fma_f32 v[68:69], v[172:173], v[84:85], v[68:69]
	v_pk_add_f32 v[66:67], v[168:169], v[66:67]
	v_pk_add_f32 v[68:69], v[166:167], v[68:69]
	v_add_f32_e32 v82, v70, v71
	v_add_f32_e32 v83, v72, v73
	v_add_f32_e32 v82, v82, v83
	v_add_f32_e32 v83, v66, v67
	v_add_f32_e32 v84, v68, v69
	v_add_f32_e32 v83, v83, v84
	v_add_f32_e32 v82, v82, v83
	v_mul_f32_e32 v83, v71, v71
	v_mul_f32_e32 v84, v73, v73
	v_fmac_f32_e32 v83, v70, v70
	v_fmac_f32_e32 v84, v72, v72
	v_add_f32_e32 v83, v83, v84
	v_mul_f32_e32 v84, v67, v67
	v_mul_f32_e32 v85, v69, v69
	v_fmac_f32_e32 v84, v66, v66
	v_fmac_f32_e32 v85, v68, v68
	v_add_f32_e32 v84, v84, v85
	v_add_f32_e32 v83, v83, v84
	v_add_f32_e32 v82, v96, v82
	v_add_f32_e32 v83, v97, v83
	global_store_dwordx4 v[92:93], v[70:73], off offset:512 nt
	global_store_dwordx4 v[92:93], v[66:69], off offset:528 nt
	s_nop 0
	v_cvt_pk_bf16_f32 v70, v70, v71
	v_cvt_pk_bf16_f32 v71, v72, v73
	v_cvt_pk_bf16_f32 v72, v66, v67
	ds_bpermute_b32 v66, v133, v82
	ds_bpermute_b32 v67, v133, v83
	v_cvt_pk_bf16_f32 v73, v68, v69
	global_store_dwordx4 v[94:95], v[70:73], off offset:256
	s_waitcnt lgkmcnt(1)
	v_add_f32_e32 v66, v82, v66
	s_waitcnt lgkmcnt(0)
	v_add_f32_e32 v67, v83, v67
	ds_bpermute_b32 v68, v136, v66
	ds_bpermute_b32 v69, v136, v67
	s_and_saveexec_b64 s[24:25], s[40:41]
	s_cbranch_execz .LBB0_738
; __device__ __forceinline__ unsigned cvt_pk_bf16(float lo, float hi) { unsigned r; asm volatile("v_cvt_pk_bf16_f32 %0, %1, %2" : "=v"(r) : "v"(lo), "v"(hi)); return r; }
; __device__ __forceinline__ void stats_mr(const f32x2 s, float& mu, float& r) { mu = s.x * (1.0f / 1024.0f); const float var = s.y * (1.0f / 1024.0f) - mu * mu; r = __builtin_amdgcn_rsqf(var + 1e-5f); }
;     __device__ __forceinline__ void operator()(const f32x4 (&acc)[2][2][4][2], const Unit& u, int wr, int wc, int fr, int fq) const {
;     ...
;         for (int g = 0; g < 8; ++g) { const int ai = g >> 2, m = g & 3; const int rr = ai * HALF + m * 16, rn = ((g + 1) >> 2) * HALF + ((g + 1) & 3) * 16;
;             f32x2 sv_n = sv_c; if (g + 1 < 8) sv_n = *(const f32x2*)(sp + (size_t)rn * 8 + ls);
;             float mu, r; stats_mr(sv_c, mu, r); float s1 = 0.f, s2 = 0.f;
; #pragma unroll
;             for (int bj = 0; bj < 2; ++bj) { const size_t ro = (size_t)rr * ldc + bj * HALF;
;                 f32x4 q0 = p0, q1 = p1;
;                 if (bj == 0) { q0 = *(const f32x4*)(bp + (ro + HALF) * 4 + l4); q1 = *(const f32x4*)(bp + (ro + HALF) * 4 + l4 + 16); }
;                 else if (g + 1 < 8) { q0 = *(const f32x4*)(bp + (size_t)rn * ldc * 4 + l4); q1 = *(const f32x4*)(bp + (size_t)rn * ldc * 4 + l4 + 16); }
;                 const f32x4 z0 = gv[bj][0] * ((p0 - mu) * r) + acc[ai][bj][m][0] + cv[bj][0], z1 = gv[bj][1] * ((p1 - mu) * r) + acc[ai][bj][m][1] + cv[bj][1];
;                 *(f32x4*)(op + ro * 4 + l4) = z0; *(f32x4*)(op + ro * 4 + l4 + 16) = z1;
;                 s1 += ((z0[0] + z0[1]) + (z0[2] + z0[3])) + ((z1[0] + z1[1]) + (z1[2] + z1[3]));
;                 s2 += ((z0[0] * z0[0] + z0[1] * z0[1]) + (z0[2] * z0[2] + z0[3] * z0[3])) + ((z1[0] * z1[0] + z1[1] * z1[1]) + (z1[2] * z1[2] + z1[3] * z1[3]));
;                 if (zb) { u32x4 w; w.x = cvt_pk_bf16(z0[0], z0[1]); w.y = cvt_pk_bf16(z0[2], z0[3]); w.z = cvt_pk_bf16(z1[0], z1[1]); w.w = cvt_pk_bf16(z1[2], z1[3]); *(u32x4*)(zp + ro * 2 + l2) = w; }
;                 p0 = q0; p1 = q1; }
;             s1 += __shfl_xor(s1, 16); s2 += __shfl_xor(s2, 16); s1 += __shfl_xor(s1, 32); s2 += __shfl_xor(s2, 32);
;             if (fq == 0) { atomicAdd(osp + 2 * (rr + fr), s1); atomicAdd(osp + 2 * (rr + fr) + 1, s2); }
;             sv_c = sv_n; }
	s_waitcnt lgkmcnt(1)
	v_add_f32_e32 v66, v66, v68
	s_waitcnt lgkmcnt(0)
	v_add_f32_e32 v67, v67, v69
	global_atomic_add_f32 v137, v66, s[82:83] offset:384
	global_atomic_add_f32 v137, v67, s[82:83] offset:388
.LBB0_738:
	s_or_b64 exec, exec, s[24:25]
	v_pk_mul_f32 v[86:87], v[98:99], s[54:55] op_sel_hi:[1,0]
	s_mov_b64 s[24:25], 0x80200
	v_fma_f32 v66, -v86, v86, v87
	v_add_f32_e32 v66, 0x3727c5ac, v66
	v_rsq_f32_e32 v84, v66
	v_lshl_add_u64 v[66:67], v[202:203], 0, s[24:25]
	global_load_dwordx2 v[82:83], v[204:205], off offset:1152
	global_load_dwordx4 v[70:73], v[90:91], off offset:512
	s_waitcnt lgkmcnt(0)
	global_load_dwordx4 v[66:69], v[66:67], off offset:16
	s_waitcnt vmcnt(7)
	v_sub_f32_e32 v79, v79, v86
	v_sub_f32_e32 v78, v78, v86
	v_sub_f32_e32 v81, v81, v86
	v_sub_f32_e32 v80, v80, v86
	v_pk_mul_f32 v[80:81], v[84:85], v[80:81] op_sel_hi:[0,1]
	v_pk_mul_f32 v[78:79], v[84:85], v[78:79] op_sel_hi:[0,1]
	s_waitcnt vmcnt(6)
	v_sub_f32_e32 v75, v75, v86
	v_sub_f32_e32 v74, v74, v86
	v_sub_f32_e32 v77, v77, v86
	v_sub_f32_e32 v76, v76, v86
	v_pk_fma_f32 v[62:63], v[170:171], v[78:79], v[62:63]
	v_pk_fma_f32 v[64:65], v[162:163], v[80:81], v[64:65]
	v_pk_mul_f32 v[76:77], v[84:85], v[76:77] op_sel_hi:[0,1]
	v_pk_mul_f32 v[74:75], v[84:85], v[74:75] op_sel_hi:[0,1]
	v_pk_add_f32 v[64:65], v[186:187], v[64:65]
	v_pk_add_f32 v[62:63], v[188:189], v[62:63]
	v_pk_fma_f32 v[58:59], v[196:197], v[74:75], v[58:59]
	v_pk_fma_f32 v[60:61], v[194:195], v[76:77], v[60:61]
	v_pk_add_f32 v[58:59], v[192:193], v[58:59]
	v_pk_add_f32 v[60:61], v[190:191], v[60:61]
	v_add_f32_e32 v74, v62, v63
	v_add_f32_e32 v75, v64, v65
	v_add_f32_e32 v74, v74, v75
	v_add_f32_e32 v75, v58, v59
	v_add_f32_e32 v78, v60, v61
	v_add_f32_e32 v75, v75, v78
	v_add_f32_e32 v74, v74, v75
	v_add_f32_e32 v80, 0, v74
	v_mul_f32_e32 v74, v63, v63
	v_mul_f32_e32 v75, v65, v65
	v_fmac_f32_e32 v74, v62, v62
	v_fmac_f32_e32 v75, v64, v64
	v_add_co_u32_e32 v76, vcc, s1, v200
	v_add_f32_e32 v74, v74, v75
	v_mul_f32_e32 v75, v59, v59
	v_mul_f32_e32 v78, v61, v61
	v_addc_co_u32_e32 v77, vcc, 0, v201, vcc
	v_fmac_f32_e32 v75, v58, v58
	v_fmac_f32_e32 v78, v60, v60
	s_mov_b32 s1, 0x40000
	v_add_f32_e32 v75, v75, v78
	v_add_co_u32_e32 v78, vcc, s1, v198
	v_add_f32_e32 v81, v74, v75
	s_nop 0
	v_addc_co_u32_e32 v79, vcc, 0, v199, vcc
	v_add_co_u32_e32 v74, vcc, s5, v202
	global_store_dwordx4 v[76:77], v[62:65], off nt
	global_store_dwordx4 v[76:77], v[58:61], off offset:16 nt
	v_addc_co_u32_e32 v75, vcc, 0, v203, vcc
	v_cvt_pk_bf16_f32 v62, v62, v63
	v_cvt_pk_bf16_f32 v63, v64, v65
	v_cvt_pk_bf16_f32 v64, v58, v59
	v_cvt_pk_bf16_f32 v65, v60, v61
	global_store_dwordx4 v[78:79], v[62:65], off
	v_lshl_add_u64 v[58:59], v[202:203], 0, s[28:29]
	global_load_dwordx4 v[62:65], v[74:75], off
	s_nop 0
	global_load_dwordx4 v[58:61], v[58:59], off offset:16
	s_waitcnt vmcnt(6)
	v_sub_f32_e32 v71, v71, v86
	v_sub_f32_e32 v70, v70, v86
	v_sub_f32_e32 v73, v73, v86
	v_sub_f32_e32 v72, v72, v86
	v_pk_mul_f32 v[72:73], v[84:85], v[72:73] op_sel_hi:[0,1]
	v_pk_mul_f32 v[70:71], v[84:85], v[70:71] op_sel_hi:[0,1]
	s_waitcnt vmcnt(5)
	v_sub_f32_e32 v67, v67, v86
	v_sub_f32_e32 v66, v66, v86
	v_sub_f32_e32 v69, v69, v86
	v_sub_f32_e32 v68, v68, v86
	v_pk_fma_f32 v[54:55], v[164:165], v[70:71], v[54:55]
	v_pk_fma_f32 v[56:57], v[160:161], v[72:73], v[56:57]
	v_pk_mul_f32 v[68:69], v[84:85], v[68:69] op_sel_hi:[0,1]
	v_pk_mul_f32 v[66:67], v[84:85], v[66:67] op_sel_hi:[0,1]
	v_pk_add_f32 v[56:57], v[174:175], v[56:57]
	v_pk_add_f32 v[54:55], v[176:177], v[54:55]
	v_pk_fma_f32 v[50:51], v[178:179], v[66:67], v[50:51]
	v_pk_fma_f32 v[52:53], v[172:173], v[68:69], v[52:53]
	v_pk_add_f32 v[50:51], v[168:169], v[50:51]
	v_pk_add_f32 v[52:53], v[166:167], v[52:53]
	v_add_f32_e32 v66, v54, v55
	v_add_f32_e32 v67, v56, v57
	v_add_f32_e32 v66, v66, v67
	v_add_f32_e32 v67, v50, v51
	v_add_f32_e32 v68, v52, v53
	v_add_f32_e32 v67, v67, v68
	v_add_f32_e32 v66, v66, v67
	v_mul_f32_e32 v67, v55, v55
	v_mul_f32_e32 v68, v57, v57
	v_fmac_f32_e32 v67, v54, v54
	v_fmac_f32_e32 v68, v56, v56
	v_add_f32_e32 v67, v67, v68
	v_mul_f32_e32 v68, v51, v51
	v_mul_f32_e32 v69, v53, v53
	v_fmac_f32_e32 v68, v50, v50
	v_fmac_f32_e32 v69, v52, v52
	v_add_f32_e32 v68, v68, v69
	v_add_f32_e32 v67, v67, v68
	v_add_f32_e32 v66, v80, v66
	v_add_f32_e32 v67, v81, v67
	global_store_dwordx4 v[76:77], v[54:57], off offset:512 nt
	global_store_dwordx4 v[76:77], v[50:53], off offset:528 nt
	s_nop 0
	v_cvt_pk_bf16_f32 v54, v54, v55
	v_cvt_pk_bf16_f32 v55, v56, v57
	v_cvt_pk_bf16_f32 v56, v50, v51
	ds_bpermute_b32 v50, v133, v66
	ds_bpermute_b32 v51, v133, v67
	v_cvt_pk_bf16_f32 v57, v52, v53
	global_store_dwordx4 v[78:79], v[54:57], off offset:256
	s_waitcnt lgkmcnt(1)
	v_add_f32_e32 v50, v66, v50
	s_waitcnt lgkmcnt(0)
	v_add_f32_e32 v51, v67, v51
	ds_bpermute_b32 v52, v136, v50
	ds_bpermute_b32 v53, v136, v51
	s_and_saveexec_b64 s[24:25], s[40:41]
	s_cbranch_execz .LBB0_740
	s_waitcnt lgkmcnt(1)
	v_add_f32_e32 v50, v50, v52
	s_waitcnt lgkmcnt(0)
	v_add_f32_e32 v51, v51, v53
	global_atomic_add_f32 v137, v50, s[82:83] offset:1024
	global_atomic_add_f32 v137, v51, s[82:83] offset:1028
; __device__ __forceinline__ unsigned cvt_pk_bf16(float lo, float hi) { unsigned r; asm volatile("v_cvt_pk_bf16_f32 %0, %1, %2" : "=v"(r) : "v"(lo), "v"(hi)); return r; }
; __device__ __forceinline__ void stats_mr(const f32x2 s, float& mu, float& r) { mu = s.x * (1.0f / 1024.0f); const float var = s.y * (1.0f / 1024.0f) - mu * mu; r = __builtin_amdgcn_rsqf(var + 1e-5f); }
;     __device__ __forceinline__ void operator()(const f32x4 (&acc)[2][2][4][2], const Unit& u, int wr, int wc, int fr, int fq) const {
;     ...
;         for (int g = 0; g < 8; ++g) { const int ai = g >> 2, m = g & 3; const int rr = ai * HALF + m * 16, rn = ((g + 1) >> 2) * HALF + ((g + 1) & 3) * 16;
;             f32x2 sv_n = sv_c; if (g + 1 < 8) sv_n = *(const f32x2*)(sp + (size_t)rn * 8 + ls);
;             float mu, r; stats_mr(sv_c, mu, r); float s1 = 0.f, s2 = 0.f;
; #pragma unroll
;             for (int bj = 0; bj < 2; ++bj) { const size_t ro = (size_t)rr * ldc + bj * HALF;
;                 f32x4 q0 = p0, q1 = p1;
;                 if (bj == 0) { q0 = *(const f32x4*)(bp + (ro + HALF) * 4 + l4); q1 = *(const f32x4*)(bp + (ro + HALF) * 4 + l4 + 16); }
;                 else if (g + 1 < 8) { q0 = *(const f32x4*)(bp + (size_t)rn * ldc * 4 + l4); q1 = *(const f32x4*)(bp + (size_t)rn * ldc * 4 + l4 + 16); }
;                 const f32x4 z0 = gv[bj][0] * ((p0 - mu) * r) + acc[ai][bj][m][0] + cv[bj][0], z1 = gv[bj][1] * ((p1 - mu) * r) + acc[ai][bj][m][1] + cv[bj][1];
;                 *(f32x4*)(op + ro * 4 + l4) = z0; *(f32x4*)(op + ro * 4 + l4 + 16) = z1;
;                 s1 += ((z0[0] + z0[1]) + (z0[2] + z0[3])) + ((z1[0] + z1[1]) + (z1[2] + z1[3]));
;                 s2 += ((z0[0] * z0[0] + z0[1] * z0[1]) + (z0[2] * z0[2] + z0[3] * z0[3])) + ((z1[0] * z1[0] + z1[1] * z1[1]) + (z1[2] * z1[2] + z1[3] * z1[3]));
;                 if (zb) { u32x4 w; w.x = cvt_pk_bf16(z0[0], z0[1]); w.y = cvt_pk_bf16(z0[2], z0[3]); w.z = cvt_pk_bf16(z1[0], z1[1]); w.w = cvt_pk_bf16(z1[2], z1[3]); *(u32x4*)(zp + ro * 2 + l2) = w; }
;                 p0 = q0; p1 = q1; }
;             s1 += __shfl_xor(s1, 16); s2 += __shfl_xor(s2, 16); s1 += __shfl_xor(s1, 32); s2 += __shfl_xor(s2, 32);
;             if (fq == 0) { atomicAdd(osp + 2 * (rr + fr), s1); atomicAdd(osp + 2 * (rr + fr) + 1, s2); }
;             sv_c = sv_n; }
.LBB0_740:
	s_or_b64 exec, exec, s[24:25]
	v_pk_mul_f32 v[70:71], v[82:83], s[54:55] op_sel_hi:[1,0]
	s_mov_b64 s[24:25], 0x90200
	v_fma_f32 v50, -v70, v70, v71
	v_add_f32_e32 v50, 0x3727c5ac, v50
	v_rsq_f32_e32 v68, v50
	v_lshl_add_u64 v[50:51], v[202:203], 0, s[24:25]
	global_load_dwordx2 v[66:67], v[204:205], off offset:1280
	global_load_dwordx4 v[54:57], v[74:75], off offset:512
	s_waitcnt lgkmcnt(0)
	global_load_dwordx4 v[50:53], v[50:51], off offset:16
	s_waitcnt vmcnt(7)
	v_sub_f32_e32 v63, v63, v70
	v_sub_f32_e32 v62, v62, v70
	v_sub_f32_e32 v65, v65, v70
	v_sub_f32_e32 v64, v64, v70
	v_pk_mul_f32 v[64:65], v[68:69], v[64:65] op_sel_hi:[0,1]
	v_pk_mul_f32 v[62:63], v[68:69], v[62:63] op_sel_hi:[0,1]
	s_waitcnt vmcnt(6)
	v_sub_f32_e32 v59, v59, v70
	v_sub_f32_e32 v58, v58, v70
	v_sub_f32_e32 v61, v61, v70
	v_sub_f32_e32 v60, v60, v70
	v_pk_fma_f32 v[46:47], v[170:171], v[62:63], v[46:47]
	v_pk_fma_f32 v[48:49], v[162:163], v[64:65], v[48:49]
	v_pk_mul_f32 v[60:61], v[68:69], v[60:61] op_sel_hi:[0,1]
	v_pk_mul_f32 v[58:59], v[68:69], v[58:59] op_sel_hi:[0,1]
	v_pk_add_f32 v[48:49], v[186:187], v[48:49]
	v_pk_add_f32 v[46:47], v[188:189], v[46:47]
	v_pk_fma_f32 v[42:43], v[196:197], v[58:59], v[42:43]
	v_pk_fma_f32 v[44:45], v[194:195], v[60:61], v[44:45]
	v_pk_add_f32 v[42:43], v[192:193], v[42:43]
	v_pk_add_f32 v[44:45], v[190:191], v[44:45]
	v_add_f32_e32 v58, v46, v47
	v_add_f32_e32 v59, v48, v49
	v_add_f32_e32 v58, v58, v59
	v_add_f32_e32 v59, v42, v43
	v_add_f32_e32 v62, v44, v45
	v_add_f32_e32 v59, v59, v62
	v_add_f32_e32 v58, v58, v59
	v_add_f32_e32 v64, 0, v58
	v_mul_f32_e32 v58, v47, v47
	v_mul_f32_e32 v59, v49, v49
	v_fmac_f32_e32 v58, v46, v46
	v_fmac_f32_e32 v59, v48, v48
	v_add_co_u32_e32 v60, vcc, s5, v200
	v_add_f32_e32 v58, v58, v59
	v_mul_f32_e32 v59, v43, v43
	v_mul_f32_e32 v62, v45, v45
	v_addc_co_u32_e32 v61, vcc, 0, v201, vcc
	v_fmac_f32_e32 v59, v42, v42
	v_fmac_f32_e32 v62, v44, v44
	s_mov_b32 s1, 0x48000
	v_add_f32_e32 v59, v59, v62
	v_add_co_u32_e32 v62, vcc, s1, v198
	s_mov_b32 s1, 0xa0000
	s_nop 0
	v_addc_co_u32_e32 v63, vcc, 0, v199, vcc
	v_add_f32_e32 v65, v58, v59
	s_mov_b64 s[4:5], 0xa0000
	v_add_co_u32_e32 v58, vcc, s1, v202
	global_store_dwordx4 v[60:61], v[46:49], off nt
	global_store_dwordx4 v[60:61], v[42:45], off offset:16 nt
	v_addc_co_u32_e32 v59, vcc, 0, v203, vcc
	v_cvt_pk_bf16_f32 v46, v46, v47
	v_cvt_pk_bf16_f32 v47, v48, v49
	v_cvt_pk_bf16_f32 v48, v42, v43
	v_cvt_pk_bf16_f32 v49, v44, v45
	global_store_dwordx4 v[62:63], v[46:49], off
	v_lshl_add_u64 v[42:43], v[202:203], 0, s[4:5]
	global_load_dwordx4 v[46:49], v[58:59], off
	s_nop 0
	global_load_dwordx4 v[42:45], v[42:43], off offset:16
	s_waitcnt vmcnt(6)
	v_sub_f32_e32 v55, v55, v70
	v_sub_f32_e32 v54, v54, v70
	v_sub_f32_e32 v57, v57, v70
	v_sub_f32_e32 v56, v56, v70
	v_pk_mul_f32 v[56:57], v[68:69], v[56:57] op_sel_hi:[0,1]
	v_pk_mul_f32 v[54:55], v[68:69], v[54:55] op_sel_hi:[0,1]
	s_waitcnt vmcnt(5)
	v_sub_f32_e32 v51, v51, v70
	v_sub_f32_e32 v50, v50, v70
	v_sub_f32_e32 v53, v53, v70
	v_sub_f32_e32 v52, v52, v70
	v_pk_fma_f32 v[38:39], v[164:165], v[54:55], v[38:39]
	v_pk_fma_f32 v[40:41], v[160:161], v[56:57], v[40:41]
	v_pk_mul_f32 v[52:53], v[68:69], v[52:53] op_sel_hi:[0,1]
	v_pk_mul_f32 v[50:51], v[68:69], v[50:51] op_sel_hi:[0,1]
	v_pk_add_f32 v[40:41], v[174:175], v[40:41]
	v_pk_add_f32 v[38:39], v[176:177], v[38:39]
	v_pk_fma_f32 v[34:35], v[178:179], v[50:51], v[34:35]
	v_pk_fma_f32 v[36:37], v[172:173], v[52:53], v[36:37]
	v_pk_add_f32 v[34:35], v[168:169], v[34:35]
	v_pk_add_f32 v[36:37], v[166:167], v[36:37]
	v_add_f32_e32 v50, v38, v39
	v_add_f32_e32 v51, v40, v41
	v_add_f32_e32 v50, v50, v51
	v_add_f32_e32 v51, v34, v35
	v_add_f32_e32 v52, v36, v37
	v_add_f32_e32 v51, v51, v52
	v_add_f32_e32 v50, v50, v51
	v_mul_f32_e32 v51, v39, v39
	v_mul_f32_e32 v52, v41, v41
	v_fmac_f32_e32 v51, v38, v38
	v_fmac_f32_e32 v52, v40, v40
	v_add_f32_e32 v51, v51, v52
	v_mul_f32_e32 v52, v35, v35
	v_mul_f32_e32 v53, v37, v37
	v_fmac_f32_e32 v52, v34, v34
	v_fmac_f32_e32 v53, v36, v36
	v_add_f32_e32 v52, v52, v53
	v_add_f32_e32 v51, v51, v52
	v_add_f32_e32 v50, v64, v50
	v_add_f32_e32 v51, v65, v51
	global_store_dwordx4 v[60:61], v[38:41], off offset:512 nt
	global_store_dwordx4 v[60:61], v[34:37], off offset:528 nt
	s_nop 0
	v_cvt_pk_bf16_f32 v38, v38, v39
	v_cvt_pk_bf16_f32 v39, v40, v41
	v_cvt_pk_bf16_f32 v40, v34, v35
	ds_bpermute_b32 v34, v133, v50
	ds_bpermute_b32 v35, v133, v51
	v_cvt_pk_bf16_f32 v41, v36, v37
	global_store_dwordx4 v[62:63], v[38:41], off offset:256
	s_waitcnt lgkmcnt(1)
	v_add_f32_e32 v34, v50, v34
	s_waitcnt lgkmcnt(0)
	v_add_f32_e32 v35, v51, v35
	ds_bpermute_b32 v36, v136, v34
	ds_bpermute_b32 v37, v136, v35
	s_and_saveexec_b64 s[24:25], s[40:41]
	s_cbranch_execz .LBB0_742
	s_waitcnt lgkmcnt(1)
	v_add_f32_e32 v34, v34, v36
	s_waitcnt lgkmcnt(0)
	v_add_f32_e32 v35, v35, v37
	global_atomic_add_f32 v137, v34, s[82:83] offset:1152
	global_atomic_add_f32 v137, v35, s[82:83] offset:1156
; __device__ __forceinline__ unsigned cvt_pk_bf16(float lo, float hi) { unsigned r; asm volatile("v_cvt_pk_bf16_f32 %0, %1, %2" : "=v"(r) : "v"(lo), "v"(hi)); return r; }
; __device__ __forceinline__ void stats_mr(const f32x2 s, float& mu, float& r) { mu = s.x * (1.0f / 1024.0f); const float var = s.y * (1.0f / 1024.0f) - mu * mu; r = __builtin_amdgcn_rsqf(var + 1e-5f); }
;     __device__ __forceinline__ void operator()(const f32x4 (&acc)[2][2][4][2], const Unit& u, int wr, int wc, int fr, int fq) const {
;     ...
;         for (int g = 0; g < 8; ++g) { const int ai = g >> 2, m = g & 3; const int rr = ai * HALF + m * 16, rn = ((g + 1) >> 2) * HALF + ((g + 1) & 3) * 16;
;             f32x2 sv_n = sv_c; if (g + 1 < 8) sv_n = *(const f32x2*)(sp + (size_t)rn * 8 + ls);
;             float mu, r; stats_mr(sv_c, mu, r); float s1 = 0.f, s2 = 0.f;
; #pragma unroll
;             for (int bj = 0; bj < 2; ++bj) { const size_t ro = (size_t)rr * ldc + bj * HALF;
;                 f32x4 q0 = p0, q1 = p1;
;                 if (bj == 0) { q0 = *(const f32x4*)(bp + (ro + HALF) * 4 + l4); q1 = *(const f32x4*)(bp + (ro + HALF) * 4 + l4 + 16); }
;                 else if (g + 1 < 8) { q0 = *(const f32x4*)(bp + (size_t)rn * ldc * 4 + l4); q1 = *(const f32x4*)(bp + (size_t)rn * ldc * 4 + l4 + 16); }
;                 const f32x4 z0 = gv[bj][0] * ((p0 - mu) * r) + acc[ai][bj][m][0] + cv[bj][0], z1 = gv[bj][1] * ((p1 - mu) * r) + acc[ai][bj][m][1] + cv[bj][1];
;                 *(f32x4*)(op + ro * 4 + l4) = z0; *(f32x4*)(op + ro * 4 + l4 + 16) = z1;
;                 s1 += ((z0[0] + z0[1]) + (z0[2] + z0[3])) + ((z1[0] + z1[1]) + (z1[2] + z1[3]));
;                 s2 += ((z0[0] * z0[0] + z0[1] * z0[1]) + (z0[2] * z0[2] + z0[3] * z0[3])) + ((z1[0] * z1[0] + z1[1] * z1[1]) + (z1[2] * z1[2] + z1[3] * z1[3]));
;                 if (zb) { u32x4 w; w.x = cvt_pk_bf16(z0[0], z0[1]); w.y = cvt_pk_bf16(z0[2], z0[3]); w.z = cvt_pk_bf16(z1[0], z1[1]); w.w = cvt_pk_bf16(z1[2], z1[3]); *(u32x4*)(zp + ro * 2 + l2) = w; }
;                 p0 = q0; p1 = q1; }
;             s1 += __shfl_xor(s1, 16); s2 += __shfl_xor(s2, 16); s1 += __shfl_xor(s1, 32); s2 += __shfl_xor(s2, 32);
;             if (fq == 0) { atomicAdd(osp + 2 * (rr + fr), s1); atomicAdd(osp + 2 * (rr + fr) + 1, s2); }
;             sv_c = sv_n; }
.LBB0_742:
	s_or_b64 exec, exec, s[24:25]
	v_pk_mul_f32 v[54:55], v[66:67], s[54:55] op_sel_hi:[1,0]
	s_mov_b64 s[4:5], 0xa0200
	v_fma_f32 v34, -v54, v54, v55
	v_add_f32_e32 v34, 0x3727c5ac, v34
	v_rsq_f32_e32 v52, v34
	v_lshl_add_u64 v[34:35], v[202:203], 0, s[4:5]
	global_load_dwordx2 v[50:51], v[204:205], off offset:1408
	global_load_dwordx4 v[38:41], v[58:59], off offset:512
	s_waitcnt lgkmcnt(0)
	global_load_dwordx4 v[34:37], v[34:35], off offset:16
	s_waitcnt vmcnt(7)
	v_sub_f32_e32 v47, v47, v54
	v_sub_f32_e32 v46, v46, v54
	v_sub_f32_e32 v49, v49, v54
	v_sub_f32_e32 v48, v48, v54
	v_pk_mul_f32 v[48:49], v[52:53], v[48:49] op_sel_hi:[0,1]
	v_pk_mul_f32 v[46:47], v[52:53], v[46:47] op_sel_hi:[0,1]
	s_waitcnt vmcnt(6)
	v_sub_f32_e32 v43, v43, v54
	v_sub_f32_e32 v42, v42, v54
	v_sub_f32_e32 v45, v45, v54
	v_sub_f32_e32 v44, v44, v54
	v_pk_fma_f32 v[30:31], v[170:171], v[46:47], v[30:31]
	v_pk_fma_f32 v[32:33], v[162:163], v[48:49], v[32:33]
	v_pk_mul_f32 v[44:45], v[52:53], v[44:45] op_sel_hi:[0,1]
	v_pk_mul_f32 v[42:43], v[52:53], v[42:43] op_sel_hi:[0,1]
	v_pk_add_f32 v[32:33], v[186:187], v[32:33]
	v_pk_add_f32 v[30:31], v[188:189], v[30:31]
	v_pk_fma_f32 v[26:27], v[196:197], v[42:43], v[26:27]
	v_pk_fma_f32 v[28:29], v[194:195], v[44:45], v[28:29]
	v_pk_add_f32 v[26:27], v[192:193], v[26:27]
	v_pk_add_f32 v[28:29], v[190:191], v[28:29]
	v_add_f32_e32 v44, v30, v31
	v_add_f32_e32 v45, v32, v33
	v_add_f32_e32 v44, v44, v45
	v_add_f32_e32 v45, v26, v27
	v_add_f32_e32 v46, v28, v29
	v_add_f32_e32 v45, v45, v46
	v_add_f32_e32 v44, v44, v45
	v_add_f32_e32 v48, 0, v44
	v_mul_f32_e32 v44, v31, v31
	v_mul_f32_e32 v45, v33, v33
	v_fmac_f32_e32 v44, v30, v30
	v_fmac_f32_e32 v45, v32, v32
	v_add_f32_e32 v44, v44, v45
	v_mul_f32_e32 v45, v27, v27
	v_mul_f32_e32 v46, v29, v29
	v_add_co_u32_e32 v42, vcc, s1, v200
	v_fmac_f32_e32 v45, v26, v26
	v_fmac_f32_e32 v46, v28, v28
	v_addc_co_u32_e32 v43, vcc, 0, v201, vcc
	v_add_f32_e32 v45, v45, v46
	s_mov_b32 s1, 0x50000
	v_add_f32_e32 v49, v44, v45
	v_add_co_u32_e32 v44, vcc, s1, v198
	s_mov_b32 s1, 0xb0000
	s_nop 0
	v_addc_co_u32_e32 v45, vcc, 0, v199, vcc
	s_mov_b64 s[4:5], 0xb0000
	v_add_co_u32_e32 v46, vcc, s1, v202
	global_store_dwordx4 v[42:43], v[30:33], off nt
	global_store_dwordx4 v[42:43], v[26:29], off offset:16 nt
	v_addc_co_u32_e32 v47, vcc, 0, v203, vcc
	v_cvt_pk_bf16_f32 v30, v30, v31
	v_cvt_pk_bf16_f32 v31, v32, v33
	v_cvt_pk_bf16_f32 v32, v26, v27
	v_cvt_pk_bf16_f32 v33, v28, v29
	global_store_dwordx4 v[44:45], v[30:33], off
	v_lshl_add_u64 v[26:27], v[202:203], 0, s[4:5]
	global_load_dwordx4 v[30:33], v[46:47], off
	s_nop 0
	global_load_dwordx4 v[26:29], v[26:27], off offset:16
	s_waitcnt vmcnt(6)
	v_sub_f32_e32 v39, v39, v54
	v_sub_f32_e32 v38, v38, v54
	v_sub_f32_e32 v41, v41, v54
	v_sub_f32_e32 v40, v40, v54
	v_pk_mul_f32 v[40:41], v[52:53], v[40:41] op_sel_hi:[0,1]
	v_pk_mul_f32 v[38:39], v[52:53], v[38:39] op_sel_hi:[0,1]
	s_waitcnt vmcnt(5)
	v_sub_f32_e32 v35, v35, v54
	v_sub_f32_e32 v34, v34, v54
	v_sub_f32_e32 v37, v37, v54
	v_sub_f32_e32 v36, v36, v54
	v_pk_fma_f32 v[22:23], v[164:165], v[38:39], v[22:23]
	v_pk_fma_f32 v[24:25], v[160:161], v[40:41], v[24:25]
	v_pk_mul_f32 v[36:37], v[52:53], v[36:37] op_sel_hi:[0,1]
	v_pk_mul_f32 v[34:35], v[52:53], v[34:35] op_sel_hi:[0,1]
	v_pk_add_f32 v[24:25], v[174:175], v[24:25]
	v_pk_add_f32 v[22:23], v[176:177], v[22:23]
	v_pk_fma_f32 v[18:19], v[178:179], v[34:35], v[18:19]
	v_pk_fma_f32 v[20:21], v[172:173], v[36:37], v[20:21]
	v_pk_add_f32 v[18:19], v[168:169], v[18:19]
	v_pk_add_f32 v[20:21], v[166:167], v[20:21]
	v_add_f32_e32 v34, v22, v23
	v_add_f32_e32 v35, v24, v25
	v_add_f32_e32 v34, v34, v35
	v_add_f32_e32 v35, v18, v19
	v_add_f32_e32 v36, v20, v21
	v_add_f32_e32 v35, v35, v36
	v_add_f32_e32 v34, v34, v35
	v_mul_f32_e32 v35, v23, v23
	v_mul_f32_e32 v36, v25, v25
	v_fmac_f32_e32 v35, v22, v22
	v_fmac_f32_e32 v36, v24, v24
	v_add_f32_e32 v35, v35, v36
	v_mul_f32_e32 v36, v19, v19
	v_mul_f32_e32 v37, v21, v21
	v_fmac_f32_e32 v36, v18, v18
	v_fmac_f32_e32 v37, v20, v20
	v_add_f32_e32 v36, v36, v37
	v_add_f32_e32 v35, v35, v36
	v_add_f32_e32 v34, v48, v34
	v_add_f32_e32 v35, v49, v35
	global_store_dwordx4 v[42:43], v[22:25], off offset:512 nt
	global_store_dwordx4 v[42:43], v[18:21], off offset:528 nt
	s_nop 0
	v_cvt_pk_bf16_f32 v22, v22, v23
	v_cvt_pk_bf16_f32 v23, v24, v25
	v_cvt_pk_bf16_f32 v24, v18, v19
	ds_bpermute_b32 v18, v133, v34
	ds_bpermute_b32 v19, v133, v35
	v_cvt_pk_bf16_f32 v25, v20, v21
	global_store_dwordx4 v[44:45], v[22:25], off offset:256
	s_waitcnt lgkmcnt(1)
	v_add_f32_e32 v18, v34, v18
	s_waitcnt lgkmcnt(0)
	v_add_f32_e32 v19, v35, v19
	ds_bpermute_b32 v20, v136, v18
	ds_bpermute_b32 v21, v136, v19
	s_and_saveexec_b64 s[24:25], s[40:41]
	s_cbranch_execz .LBB0_744
	s_waitcnt lgkmcnt(1)
	v_add_f32_e32 v18, v18, v20
	s_waitcnt lgkmcnt(0)
	v_add_f32_e32 v19, v19, v21
	global_atomic_add_f32 v137, v18, s[82:83] offset:1280
	global_atomic_add_f32 v137, v19, s[82:83] offset:1284
; __device__ __forceinline__ unsigned cvt_pk_bf16(float lo, float hi) { unsigned r; asm volatile("v_cvt_pk_bf16_f32 %0, %1, %2" : "=v"(r) : "v"(lo), "v"(hi)); return r; }
; __device__ __forceinline__ void stats_mr(const f32x2 s, float& mu, float& r) { mu = s.x * (1.0f / 1024.0f); const float var = s.y * (1.0f / 1024.0f) - mu * mu; r = __builtin_amdgcn_rsqf(var + 1e-5f); }
;     __device__ __forceinline__ void operator()(const f32x4 (&acc)[2][2][4][2], const Unit& u, int wr, int wc, int fr, int fq) const {
;     ...
;         for (int g = 0; g < 8; ++g) { const int ai = g >> 2, m = g & 3; const int rr = ai * HALF + m * 16, rn = ((g + 1) >> 2) * HALF + ((g + 1) & 3) * 16;
;             f32x2 sv_n = sv_c; if (g + 1 < 8) sv_n = *(const f32x2*)(sp + (size_t)rn * 8 + ls);
;             float mu, r; stats_mr(sv_c, mu, r); float s1 = 0.f, s2 = 0.f;
; #pragma unroll
;             for (int bj = 0; bj < 2; ++bj) { const size_t ro = (size_t)rr * ldc + bj * HALF;
;                 f32x4 q0 = p0, q1 = p1;
;                 if (bj == 0) { q0 = *(const f32x4*)(bp + (ro + HALF) * 4 + l4); q1 = *(const f32x4*)(bp + (ro + HALF) * 4 + l4 + 16); }
;                 else if (g + 1 < 8) { q0 = *(const f32x4*)(bp + (size_t)rn * ldc * 4 + l4); q1 = *(const f32x4*)(bp + (size_t)rn * ldc * 4 + l4 + 16); }
;                 const f32x4 z0 = gv[bj][0] * ((p0 - mu) * r) + acc[ai][bj][m][0] + cv[bj][0], z1 = gv[bj][1] * ((p1 - mu) * r) + acc[ai][bj][m][1] + cv[bj][1];
;                 *(f32x4*)(op + ro * 4 + l4) = z0; *(f32x4*)(op + ro * 4 + l4 + 16) = z1;
;                 s1 += ((z0[0] + z0[1]) + (z0[2] + z0[3])) + ((z1[0] + z1[1]) + (z1[2] + z1[3]));
;                 s2 += ((z0[0] * z0[0] + z0[1] * z0[1]) + (z0[2] * z0[2] + z0[3] * z0[3])) + ((z1[0] * z1[0] + z1[1] * z1[1]) + (z1[2] * z1[2] + z1[3] * z1[3]));
;                 if (zb) { u32x4 w; w.x = cvt_pk_bf16(z0[0], z0[1]); w.y = cvt_pk_bf16(z0[2], z0[3]); w.z = cvt_pk_bf16(z1[0], z1[1]); w.w = cvt_pk_bf16(z1[2], z1[3]); *(u32x4*)(zp + ro * 2 + l2) = w; }
;                 p0 = q0; p1 = q1; }
;             s1 += __shfl_xor(s1, 16); s2 += __shfl_xor(s2, 16); s1 += __shfl_xor(s1, 32); s2 += __shfl_xor(s2, 32);
;             if (fq == 0) { atomicAdd(osp + 2 * (rr + fr), s1); atomicAdd(osp + 2 * (rr + fr) + 1, s2); }
;             sv_c = sv_n; }
.LBB0_744:
	s_or_b64 exec, exec, s[24:25]
	s_mov_b64 s[4:5], 0xb0200
	s_waitcnt lgkmcnt(0)
	global_load_dwordx4 v[18:21], v[46:47], off offset:512
	v_lshl_add_u64 v[22:23], v[202:203], 0, s[4:5]
	global_load_dwordx4 v[22:25], v[22:23], off offset:16
	v_pk_mul_f32 v[34:35], v[50:51], s[54:55] op_sel_hi:[1,0]
	v_add_co_u32_e32 v36, vcc, s1, v200
	v_fma_f32 v35, -v34, v34, v35
	v_add_f32_e32 v35, 0x3727c5ac, v35
	v_rsq_f32_e32 v40, v35
	s_waitcnt vmcnt(6)
	v_sub_f32_e32 v31, v31, v34
	v_sub_f32_e32 v30, v30, v34
	v_sub_f32_e32 v33, v33, v34
	v_sub_f32_e32 v32, v32, v34
	s_waitcnt vmcnt(5)
	v_sub_f32_e32 v27, v27, v34
	v_sub_f32_e32 v26, v26, v34
	v_sub_f32_e32 v29, v29, v34
	v_sub_f32_e32 v28, v28, v34
	v_pk_mul_f32 v[32:33], v[40:41], v[32:33] op_sel_hi:[0,1]
	v_pk_mul_f32 v[30:31], v[40:41], v[30:31] op_sel_hi:[0,1]
	v_pk_mul_f32 v[28:29], v[40:41], v[28:29] op_sel_hi:[0,1]
	v_pk_mul_f32 v[26:27], v[40:41], v[26:27] op_sel_hi:[0,1]
	v_pk_fma_f32 v[14:15], v[170:171], v[30:31], v[14:15]
	v_pk_fma_f32 v[16:17], v[162:163], v[32:33], v[16:17]
	v_pk_fma_f32 v[26:27], v[196:197], v[26:27], v[10:11]
	v_pk_fma_f32 v[28:29], v[194:195], v[28:29], v[12:13]
	v_pk_add_f32 v[12:13], v[186:187], v[16:17]
	v_pk_add_f32 v[10:11], v[188:189], v[14:15]
	v_pk_add_f32 v[16:17], v[190:191], v[28:29]
	v_pk_add_f32 v[14:15], v[192:193], v[26:27]
	v_addc_co_u32_e32 v37, vcc, 0, v201, vcc
	s_mov_b32 s1, 0x58000
	v_add_f32_e32 v30, v10, v11
	v_add_f32_e32 v31, v12, v13
	v_add_f32_e32 v32, v14, v15
	v_add_f32_e32 v33, v16, v17
	v_mul_f32_e32 v35, v11, v11
	v_mul_f32_e32 v41, v13, v13
	v_mul_f32_e32 v42, v15, v15
	v_mul_f32_e32 v43, v17, v17
	v_add_co_u32_e32 v38, vcc, s1, v198
	global_store_dwordx4 v[36:37], v[10:13], off nt
	global_store_dwordx4 v[36:37], v[14:17], off offset:16 nt
	v_cvt_pk_bf16_f32 v26, v10, v11
	v_cvt_pk_bf16_f32 v27, v12, v13
	v_fmac_f32_e32 v35, v10, v10
	v_add_f32_e32 v11, v30, v31
	v_add_f32_e32 v13, v32, v33
	v_fmac_f32_e32 v41, v12, v12
	v_fmac_f32_e32 v42, v14, v14
	v_fmac_f32_e32 v43, v16, v16
	v_addc_co_u32_e32 v39, vcc, 0, v199, vcc
	v_add_f32_e32 v10, v11, v13
	v_add_f32_e32 v11, v35, v41
	v_add_f32_e32 v12, v42, v43
	v_cvt_pk_bf16_f32 v28, v14, v15
	v_cvt_pk_bf16_f32 v29, v16, v17
	global_store_dwordx4 v[38:39], v[26:29], off
	s_waitcnt vmcnt(4)
	v_sub_f32_e32 v13, v21, v34
	v_add_f32_e32 v26, 0, v10
	v_add_f32_e32 v27, v11, v12
	v_sub_f32_e32 v11, v19, v34
	v_sub_f32_e32 v10, v18, v34
	v_sub_f32_e32 v12, v20, v34
	v_pk_mul_f32 v[12:13], v[40:41], v[12:13] op_sel_hi:[0,1]
	v_pk_mul_f32 v[10:11], v[40:41], v[10:11] op_sel_hi:[0,1]
	s_waitcnt vmcnt(3)
	v_sub_f32_e32 v15, v23, v34
	v_sub_f32_e32 v14, v22, v34
	v_sub_f32_e32 v17, v25, v34
	v_sub_f32_e32 v16, v24, v34
	v_pk_fma_f32 v[6:7], v[164:165], v[10:11], v[6:7]
	v_pk_fma_f32 v[8:9], v[160:161], v[12:13], v[8:9]
	v_pk_mul_f32 v[10:11], v[40:41], v[16:17] op_sel_hi:[0,1]
	v_pk_mul_f32 v[12:13], v[40:41], v[14:15] op_sel_hi:[0,1]
	v_pk_add_f32 v[8:9], v[174:175], v[8:9]
	v_pk_add_f32 v[6:7], v[176:177], v[6:7]
	v_pk_fma_f32 v[2:3], v[178:179], v[12:13], v[2:3]
	v_pk_fma_f32 v[4:5], v[172:173], v[10:11], v[4:5]
	v_pk_add_f32 v[10:11], v[168:169], v[2:3]
	v_pk_add_f32 v[12:13], v[166:167], v[4:5]
	v_add_f32_e32 v2, v6, v7
	v_add_f32_e32 v3, v8, v9
	v_add_f32_e32 v2, v2, v3
	v_add_f32_e32 v3, v10, v11
	v_add_f32_e32 v4, v12, v13
	v_add_f32_e32 v3, v3, v4
	v_add_f32_e32 v2, v2, v3
	v_mul_f32_e32 v3, v7, v7
	v_mul_f32_e32 v4, v9, v9
	v_fmac_f32_e32 v3, v6, v6
	v_fmac_f32_e32 v4, v8, v8
	v_add_f32_e32 v3, v3, v4
	v_mul_f32_e32 v4, v11, v11
	v_mul_f32_e32 v5, v13, v13
	v_fmac_f32_e32 v4, v10, v10
	v_fmac_f32_e32 v5, v12, v12
	v_add_f32_e32 v4, v4, v5
	v_add_f32_e32 v3, v3, v4
	v_add_f32_e32 v2, v26, v2
	v_add_f32_e32 v3, v27, v3
	ds_bpermute_b32 v4, v133, v2
	ds_bpermute_b32 v5, v133, v3
	global_store_dwordx4 v[36:37], v[6:9], off offset:512 nt
	global_store_dwordx4 v[36:37], v[10:13], off offset:528 nt
	s_waitcnt lgkmcnt(1)
	v_add_f32_e32 v2, v2, v4
	s_waitcnt lgkmcnt(0)
	v_add_f32_e32 v3, v3, v5
	ds_bpermute_b32 v4, v136, v2
	ds_bpermute_b32 v5, v136, v3
	v_cvt_pk_bf16_f32 v6, v6, v7
	v_cvt_pk_bf16_f32 v7, v8, v9
	v_cvt_pk_bf16_f32 v8, v10, v11
	v_cvt_pk_bf16_f32 v9, v12, v13
	global_store_dwordx4 v[38:39], v[6:9], off offset:256
	s_and_saveexec_b64 s[24:25], s[40:41]
	s_cbranch_execz .LBB0_746
	s_waitcnt lgkmcnt(1)
	v_add_f32_e32 v2, v2, v4
	s_waitcnt lgkmcnt(0)
	v_add_f32_e32 v3, v3, v5
	global_atomic_add_f32 v137, v2, s[82:83] offset:1408
	global_atomic_add_f32 v137, v3, s[82:83] offset:1412

;     __device__ __forceinline__ void operator()(const f32x4 (&acc)[2][2][4][2], const Unit& u, int wr, int wc, int fr, int fq) const {
;     ...
;         const int urow = u.pm * BM + wr * 64, ucol = u.pn * BM + wc * 32;
;         const size_t ubase = (size_t)urow * ldc + ucol;
;         const char* bp = (const char*)(base + ubase); char* op = (char*)(out + ubase); char* zp = (char*)(zb + ubase);
;         const char* sp = (const char*)(bstats + 2 * (size_t)urow); float* osp = ostats + 2 * (size_t)urow;
;         const unsigned l4 = (unsigned)(fr * ldc + 8 * fq) * 4u, l2 = (unsigned)(fr * ldc + 8 * fq) * 2u, ls = (unsigned)fr * 8u;
;         const int col0 = ucol + 8 * fq;
;         f32x4 gv[2][2], cv[2][2];
; #pragma unroll
;         for (int bj = 0; bj < 2; ++bj)
; #pragma unroll
;             for (int n = 0; n < 2; ++n) { gv[bj][n] = *(const f32x4*)(bg + col0 + bj * HALF + 4 * n) * alpha;
;                 cv[bj][n] = *(const f32x4*)(bb + col0 + bj * HALF + 4 * n) * alpha + *(const f32x4*)(bias + col0 + bj * HALF + 4 * n); }
;         f32x2 sv_c = *(const f32x2*)(sp + ls);
;         f32x4 p0 = *(const f32x4*)(bp + l4), p1 = *(const f32x4*)(bp + l4 + 16);
; #pragma unroll
;         for (int g = 0; g < 8; ++g) { const int ai = g >> 2, m = g & 3; const int rr = ai * HALF + m * 16, rn = ((g + 1) >> 2) * HALF + ((g + 1) & 3) * 16;
;             f32x2 sv_n = sv_c; if (g + 1 < 8) sv_n = *(const f32x2*)(sp + (size_t)rn * 8 + ls);
;             float mu, r; stats_mr(sv_c, mu, r); float s1 = 0.f, s2 = 0.f;
; #pragma unroll
;             for (int bj = 0; bj < 2; ++bj) { const size_t ro = (size_t)rr * ldc + bj * HALF;
;                 f32x4 q0 = p0, q1 = p1;
;                 if (bj == 0) { q0 = *(const f32x4*)(bp + (ro + HALF) * 4 + l4); q1 = *(const f32x4*)(bp + (ro + HALF) * 4 + l4 + 16); }
;                 else if (g + 1 < 8) { q0 = *(const f32x4*)(bp + (size_t)rn * ldc * 4 + l4); q1 = *(const f32x4*)(bp + (size_t)rn * ldc * 4 + l4 + 16); }
;                 const f32x4 z0 = gv[bj][0] * ((p0 - mu) * r) + acc[ai][bj][m][0] + cv[bj][0], z1 = gv[bj][1] * ((p1 - mu) * r) + acc[ai][bj][m][1] + cv[bj][1];
;                 *(f32x4*)(op + ro * 4 + l4) = z0; *(f32x4*)(op + ro * 4 + l4 + 16) = z1;
;                 s1 += ((z0[0] + z0[1]) + (z0[2] + z0[3])) + ((z1[0] + z1[1]) + (z1[2] + z1[3]));
.LBB0_974:
	s_lshl_b32 s4, s95, 8
	s_add_i32 s50, s4, s83
	s_lshl_b32 s4, s94, 8
	s_or_b32 s4, s4, s89
	v_or_b32_e32 v130, s4, v1
	v_ashrrev_i32_e32 v131, 31, v130
	v_lshlrev_b64 v[130:131], 2, v[130:131]
	v_lshl_add_u64 v[150:151], s[22:23], 0, v[130:131]
	v_lshl_add_u64 v[152:153], s[30:31], 0, v[130:131]
	v_lshl_add_u64 v[154:155], s[18:19], 0, v[130:131]
	global_load_dwordx4 v[130:133], v[150:151], off offset:16
	global_load_dwordx4 v[134:137], v[150:151], off
	s_ashr_i32 s51, s50, 31
	v_lshl_add_u64 v[212:213], s[50:51], 3, v[172:173]
	s_ashr_i32 s5, s4, 31
	s_lshl_b64 s[24:25], s[50:51], 10
	s_add_u32 s24, s24, s4
	s_addc_u32 s25, s25, s5
	s_lshl_b64 s[34:35], s[24:25], 2
	v_readlane_b32 s4, v253, 10
	v_readlane_b32 s5, v253, 11
	s_add_u32 s34, s4, s34
	s_addc_u32 s35, s5, s35
	v_lshl_add_u64 v[206:207], s[34:35], 0, v[174:175]
	v_lshl_add_u64 v[204:205], s[24:25], 1, v[176:177]
	s_andn2_b64 vcc, exec, s[20:21]
	s_waitcnt vmcnt(0)
	v_pk_mul_f32 v[192:193], v[132:133], s[26:27] op_sel_hi:[1,0]
	v_pk_mul_f32 v[196:197], v[136:137], s[26:27] op_sel_hi:[1,0]
	v_pk_mul_f32 v[202:203], v[134:135], s[26:27] op_sel_hi:[1,0]
	global_load_dwordx4 v[134:137], v[152:153], off offset:16
	global_load_dwordx4 v[138:141], v[152:153], off
	global_load_dwordx4 v[142:145], v[154:155], off offset:16
	global_load_dwordx4 v[146:149], v[154:155], off
	v_pk_mul_f32 v[194:195], v[130:131], s[26:27] op_sel_hi:[1,0]
	s_waitcnt vmcnt(1)
	v_pk_fma_f32 v[188:189], v[136:137], s[26:27], v[144:145] op_sel_hi:[1,0,1]
	s_waitcnt vmcnt(0)
	v_pk_fma_f32 v[198:199], v[140:141], s[26:27], v[148:149] op_sel_hi:[1,0,1]
	v_pk_fma_f32 v[200:201], v[138:139], s[26:27], v[146:147] op_sel_hi:[1,0,1]
	v_pk_fma_f32 v[190:191], v[134:135], s[26:27], v[142:143] op_sel_hi:[1,0,1]
	global_load_dwordx4 v[130:133], v[150:151], off offset:528
	global_load_dwordx4 v[146:149], v[150:151], off offset:512
	global_load_dwordx4 v[134:137], v[152:153], off offset:528
	global_load_dwordx4 v[142:145], v[152:153], off offset:512
	global_load_dwordx4 v[138:141], v[154:155], off offset:528
	s_nop 0
	global_load_dwordx4 v[150:153], v[154:155], off offset:512
	s_nop 0
	global_load_dwordx2 v[154:155], v[212:213], off
	global_load_dwordx4 v[208:211], v[206:207], off offset:16
	global_load_dwordx4 v[234:237], v[206:207], off
	global_load_dwordx2 v[214:215], v[212:213], off offset:128
	s_waitcnt vmcnt(3)
	v_pk_mul_f32 v[218:219], v[154:155], s[54:55] op_sel_hi:[1,0]
	s_nop 0
	v_fma_f32 v154, -v218, v218, v219
	v_add_f32_e32 v154, 0x3727c5ac, v154
	v_rsq_f32_e32 v216, v154
	global_load_dwordx4 v[154:157], v[206:207], off offset:528
	global_load_dwordx4 v[158:161], v[206:207], off offset:512
	s_waitcnt vmcnt(3)
	v_sub_f32_e32 v221, v235, v218
	v_sub_f32_e32 v220, v234, v218
	v_sub_f32_e32 v235, v237, v218
	v_sub_f32_e32 v234, v236, v218
	v_sub_f32_e32 v209, v209, v218
	v_sub_f32_e32 v208, v208, v218
	v_sub_f32_e32 v211, v211, v218
	v_sub_f32_e32 v210, v210, v218
	v_pk_mul_f32 v[234:235], v[234:235], v[216:217] op_sel_hi:[1,0]
	v_pk_mul_f32 v[220:221], v[220:221], v[216:217] op_sel_hi:[1,0]
	v_pk_mul_f32 v[210:211], v[210:211], v[216:217] op_sel_hi:[1,0]
	v_pk_mul_f32 v[208:209], v[208:209], v[216:217] op_sel_hi:[1,0]
	v_pk_fma_f32 v[126:127], v[202:203], v[220:221], v[126:127]
	v_pk_fma_f32 v[128:129], v[196:197], v[234:235], v[128:129]
	v_pk_fma_f32 v[122:123], v[194:195], v[208:209], v[122:123]
	v_pk_fma_f32 v[124:125], v[192:193], v[210:211], v[124:125]
	v_cndmask_b32_e64 v208, 0, 1, s[20:21]
	v_pk_add_f32 v[128:129], v[198:199], v[128:129]
	v_pk_add_f32 v[126:127], v[200:201], v[126:127]
	v_pk_add_f32 v[124:125], v[188:189], v[124:125]
	v_pk_add_f32 v[122:123], v[190:191], v[122:123]
	v_cmp_ne_u32_e64 s[42:43], 1, v208
	global_store_dwordx4 v[206:207], v[126:129], off nt
	global_store_dwordx4 v[206:207], v[122:125], off offset:16 nt
	s_cbranch_vccnz .LBB0_976
	v_cvt_pk_bf16_f32 v208, v126, v127
	v_cvt_pk_bf16_f32 v209, v128, v129
	v_cvt_pk_bf16_f32 v210, v122, v123
	v_cvt_pk_bf16_f32 v211, v124, v125
	global_store_dwordx4 v[204:205], v[208:211], off
.LBB0_976:
	v_add_co_u32_e32 v220, vcc, s77, v206
	s_mov_b64 s[4:5], 0x10000
	s_nop 0
	v_addc_co_u32_e32 v221, vcc, 0, v207, vcc
	v_pk_mul_f32 v[208:209], v[148:149], s[26:27] op_sel_hi:[1,0]
	v_pk_mul_f32 v[210:211], v[146:147], s[26:27] op_sel_hi:[1,0]
	v_pk_fma_f32 v[146:147], v[144:145], s[26:27], v[152:153] op_sel_hi:[1,0,1]
	v_pk_fma_f32 v[148:149], v[142:143], s[26:27], v[150:151] op_sel_hi:[1,0,1]
	v_pk_mul_f32 v[142:143], v[132:133], s[26:27] op_sel_hi:[1,0]
	v_pk_mul_f32 v[144:145], v[130:131], s[26:27] op_sel_hi:[1,0]
	v_pk_fma_f32 v[140:141], v[136:137], s[26:27], v[140:141] op_sel_hi:[1,0,1]
	v_pk_fma_f32 v[138:139], v[134:135], s[26:27], v[138:139] op_sel_hi:[1,0,1]
	v_lshl_add_u64 v[152:153], v[206:207], 0, s[4:5]
	global_load_dwordx4 v[134:137], v[220:221], off
	global_load_dwordx4 v[130:133], v[152:153], off offset:16
	s_waitcnt vmcnt(4)
	v_sub_f32_e32 v151, v161, v218
	v_sub_f32_e32 v150, v160, v218
	v_mov_b32_e32 v160, v216
	v_mov_b32_e32 v161, v216
	v_pk_mul_f32 v[150:151], v[150:151], v[160:161]
	v_mov_b32_e32 v217, v216
	v_sub_f32_e32 v159, v159, v218
	v_sub_f32_e32 v158, v158, v218
	v_pk_fma_f32 v[120:121], v[208:209], v[150:151], v[120:121]
	v_sub_f32_e32 v151, v155, v218
	v_sub_f32_e32 v150, v154, v218
	v_sub_f32_e32 v155, v157, v218
	v_sub_f32_e32 v154, v156, v218
	v_pk_mul_f32 v[158:159], v[158:159], v[216:217]
	v_pk_mul_f32 v[154:155], v[154:155], v[160:161]
	v_pk_mul_f32 v[150:151], v[150:151], v[216:217]
	v_pk_fma_f32 v[118:119], v[210:211], v[158:159], v[118:119]
	v_pk_fma_f32 v[114:115], v[144:145], v[150:151], v[114:115]
	v_pk_fma_f32 v[116:117], v[142:143], v[154:155], v[116:117]
	v_pk_add_f32 v[120:121], v[146:147], v[120:121]
	v_pk_add_f32 v[118:119], v[148:149], v[118:119]
	v_pk_add_f32 v[116:117], v[140:141], v[116:117]
	v_pk_add_f32 v[114:115], v[138:139], v[114:115]
	s_and_b64 vcc, exec, s[42:43]
	global_store_dwordx4 v[206:207], v[118:121], off offset:512 nt
	global_store_dwordx4 v[206:207], v[114:117], off offset:528 nt
	s_cbranch_vccnz .LBB0_978
	v_cvt_pk_bf16_f32 v154, v118, v119
	v_cvt_pk_bf16_f32 v155, v120, v121
	v_cvt_pk_bf16_f32 v156, v114, v115
	v_cvt_pk_bf16_f32 v157, v116, v117
	global_store_dwordx4 v[204:205], v[154:157], off offset:256

; __device__ __forceinline__ unsigned cvt_pk_bf16(float lo, float hi) { unsigned r; asm volatile("v_cvt_pk_bf16_f32 %0, %1, %2" : "=v"(r) : "v"(lo), "v"(hi)); return r; }
; __device__ __forceinline__ void stats_mr(const f32x2 s, float& mu, float& r) { mu = s.x * (1.0f / 1024.0f); const float var = s.y * (1.0f / 1024.0f) - mu * mu; r = __builtin_amdgcn_rsqf(var + 1e-5f); }
;     __device__ __forceinline__ void operator()(const f32x4 (&acc)[2][2][4][2], const Unit& u, int wr, int wc, int fr, int fq) const {
;     ...
;         for (int g = 0; g < 8; ++g) { const int ai = g >> 2, m = g & 3; const int rr = ai * HALF + m * 16, rn = ((g + 1) >> 2) * HALF + ((g + 1) & 3) * 16;
;             f32x2 sv_n = sv_c; if (g + 1 < 8) sv_n = *(const f32x2*)(sp + (size_t)rn * 8 + ls);
;             float mu, r; stats_mr(sv_c, mu, r); float s1 = 0.f, s2 = 0.f;
; #pragma unroll
;             for (int bj = 0; bj < 2; ++bj) { const size_t ro = (size_t)rr * ldc + bj * HALF;
;                 f32x4 q0 = p0, q1 = p1;
;                 if (bj == 0) { q0 = *(const f32x4*)(bp + (ro + HALF) * 4 + l4); q1 = *(const f32x4*)(bp + (ro + HALF) * 4 + l4 + 16); }
;                 else if (g + 1 < 8) { q0 = *(const f32x4*)(bp + (size_t)rn * ldc * 4 + l4); q1 = *(const f32x4*)(bp + (size_t)rn * ldc * 4 + l4 + 16); }
;                 const f32x4 z0 = gv[bj][0] * ((p0 - mu) * r) + acc[ai][bj][m][0] + cv[bj][0], z1 = gv[bj][1] * ((p1 - mu) * r) + acc[ai][bj][m][1] + cv[bj][1];
;                 *(f32x4*)(op + ro * 4 + l4) = z0; *(f32x4*)(op + ro * 4 + l4 + 16) = z1;
;                 s1 += ((z0[0] + z0[1]) + (z0[2] + z0[3])) + ((z1[0] + z1[1]) + (z1[2] + z1[3]));
;                 s2 += ((z0[0] * z0[0] + z0[1] * z0[1]) + (z0[2] * z0[2] + z0[3] * z0[3])) + ((z1[0] * z1[0] + z1[1] * z1[1]) + (z1[2] * z1[2] + z1[3] * z1[3]));
;                 if (zb) { u32x4 w; w.x = cvt_pk_bf16(z0[0], z0[1]); w.y = cvt_pk_bf16(z0[2], z0[3]); w.z = cvt_pk_bf16(z1[0], z1[1]); w.w = cvt_pk_bf16(z1[2], z1[3]); *(u32x4*)(zp + ro * 2 + l2) = w; }
;                 p0 = q0; p1 = q1; }
.LBB0_980:
	s_or_b64 exec, exec, s[24:25]
	s_mov_b64 s[4:5], 0x10200
	global_load_dwordx2 v[150:151], v[212:213], off offset:256
	v_lshl_add_u64 v[114:115], v[206:207], 0, s[4:5]
	global_load_dwordx4 v[126:129], v[220:221], off offset:512
	global_load_dwordx4 v[122:125], v[114:115], off offset:16
	v_pk_mul_f32 v[156:157], v[214:215], s[54:55] op_sel_hi:[1,0]
	s_nop 0
	v_fma_f32 v114, -v156, v156, v157
	v_add_f32_e32 v114, 0x3727c5ac, v114
	v_rsq_f32_e32 v154, v114
	s_waitcnt vmcnt(6)
	v_sub_f32_e32 v115, v135, v156
	v_sub_f32_e32 v114, v134, v156
	s_waitcnt lgkmcnt(0)
	v_sub_f32_e32 v117, v137, v156
	v_pk_mul_f32 v[114:115], v[154:155], v[114:115] op_sel_hi:[0,1]
	v_sub_f32_e32 v116, v136, v156
	v_pk_fma_f32 v[110:111], v[202:203], v[114:115], v[110:111]
	s_waitcnt vmcnt(5)
	v_sub_f32_e32 v115, v131, v156
	v_sub_f32_e32 v114, v130, v156
	v_pk_mul_f32 v[116:117], v[154:155], v[116:117] op_sel_hi:[0,1]
	v_pk_mul_f32 v[114:115], v[154:155], v[114:115] op_sel_hi:[0,1]
	v_pk_fma_f32 v[112:113], v[196:197], v[116:117], v[112:113]
	v_sub_f32_e32 v117, v133, v156
	v_sub_f32_e32 v116, v132, v156
	v_pk_fma_f32 v[106:107], v[194:195], v[114:115], v[106:107]
	v_pk_mul_f32 v[116:117], v[154:155], v[116:117] op_sel_hi:[0,1]
	v_pk_add_f32 v[114:115], v[190:191], v[106:107]
	v_add_co_u32_e32 v106, vcc, 0x10000, v206
	v_pk_fma_f32 v[108:109], v[192:193], v[116:117], v[108:109]
	s_nop 0
	v_addc_co_u32_e32 v107, vcc, 0, v207, vcc
	v_pk_add_f32 v[112:113], v[198:199], v[112:113]
	v_pk_add_f32 v[110:111], v[200:201], v[110:111]
	v_pk_add_f32 v[116:117], v[188:189], v[108:109]
	s_and_b64 vcc, exec, s[42:43]
	global_store_dwordx4 v[152:153], v[110:113], off nt
	global_store_dwordx4 v[106:107], v[114:117], off offset:16 nt
	s_cbranch_vccnz .LBB0_982
	v_add_co_u32_e32 v118, vcc, 0x8000, v204
	v_cvt_pk_bf16_f32 v106, v110, v111
	v_cvt_pk_bf16_f32 v107, v112, v113
	v_cvt_pk_bf16_f32 v108, v114, v115
	v_cvt_pk_bf16_f32 v109, v116, v117
	s_nop 1
	v_addc_co_u32_e32 v119, vcc, 0, v205, vcc
	global_store_dwordx4 v[118:119], v[106:109], off
.LBB0_982:
	s_nop 1
	v_add_co_u32_e32 v106, vcc, 0x20000, v206
	s_mov_b64 s[4:5], 0x20000
	s_nop 0
	v_addc_co_u32_e32 v107, vcc, 0, v207, vcc
	v_lshl_add_u64 v[130:131], v[206:207], 0, s[4:5]
	global_load_dwordx4 v[118:121], v[106:107], off
	s_nop 0
	global_load_dwordx4 v[106:109], v[130:131], off offset:16
	v_mov_b32_e32 v155, v154
	s_waitcnt vmcnt(4)
	v_sub_f32_e32 v123, v123, v156
	v_sub_f32_e32 v122, v122, v156
	v_sub_f32_e32 v127, v127, v156
	v_sub_f32_e32 v126, v126, v156
	v_sub_f32_e32 v129, v129, v156
	v_sub_f32_e32 v128, v128, v156
	v_mov_b32_e32 v132, v154
	v_mov_b32_e32 v133, v154
	v_sub_f32_e32 v125, v125, v156
	v_sub_f32_e32 v124, v124, v156
	v_pk_mul_f32 v[122:123], v[154:155], v[122:123]
	v_pk_mul_f32 v[128:129], v[132:133], v[128:129]
	v_pk_mul_f32 v[126:127], v[154:155], v[126:127]
	v_pk_mul_f32 v[124:125], v[132:133], v[124:125]
	v_pk_fma_f32 v[98:99], v[144:145], v[122:123], v[98:99]
	v_add_co_u32_e32 v122, vcc, 0x10000, v206
	v_pk_fma_f32 v[102:103], v[210:211], v[126:127], v[102:103]
	v_pk_fma_f32 v[104:105], v[208:209], v[128:129], v[104:105]
	v_pk_fma_f32 v[100:101], v[142:143], v[124:125], v[100:101]
	v_addc_co_u32_e32 v123, vcc, 0, v207, vcc
	v_pk_add_f32 v[104:105], v[146:147], v[104:105]
	v_pk_add_f32 v[102:103], v[148:149], v[102:103]
	v_pk_add_f32 v[100:101], v[140:141], v[100:101]
	v_pk_add_f32 v[98:99], v[138:139], v[98:99]
	s_and_b64 vcc, exec, s[42:43]
	global_store_dwordx4 v[122:123], v[102:105], off offset:512 nt
	global_store_dwordx4 v[122:123], v[98:101], off offset:528 nt
	s_cbranch_vccnz .LBB0_984
	v_add_co_u32_e32 v126, vcc, 0x8000, v204
	v_cvt_pk_bf16_f32 v122, v102, v103
	v_cvt_pk_bf16_f32 v123, v104, v105
	v_cvt_pk_bf16_f32 v124, v98, v99
	v_cvt_pk_bf16_f32 v125, v100, v101
	s_nop 1
	v_addc_co_u32_e32 v127, vcc, 0, v205, vcc
	global_store_dwordx4 v[126:127], v[122:125], off offset:256

; __device__ __forceinline__ unsigned cvt_pk_bf16(float lo, float hi) { unsigned r; asm volatile("v_cvt_pk_bf16_f32 %0, %1, %2" : "=v"(r) : "v"(lo), "v"(hi)); return r; }
; __device__ __forceinline__ void stats_mr(const f32x2 s, float& mu, float& r) { mu = s.x * (1.0f / 1024.0f); const float var = s.y * (1.0f / 1024.0f) - mu * mu; r = __builtin_amdgcn_rsqf(var + 1e-5f); }
;     __device__ __forceinline__ void operator()(const f32x4 (&acc)[2][2][4][2], const Unit& u, int wr, int wc, int fr, int fq) const {
;     ...
;         for (int g = 0; g < 8; ++g) { const int ai = g >> 2, m = g & 3; const int rr = ai * HALF + m * 16, rn = ((g + 1) >> 2) * HALF + ((g + 1) & 3) * 16;
;             f32x2 sv_n = sv_c; if (g + 1 < 8) sv_n = *(const f32x2*)(sp + (size_t)rn * 8 + ls);
;             float mu, r; stats_mr(sv_c, mu, r); float s1 = 0.f, s2 = 0.f;
; #pragma unroll
;             for (int bj = 0; bj < 2; ++bj) { const size_t ro = (size_t)rr * ldc + bj * HALF;
;                 f32x4 q0 = p0, q1 = p1;
;                 if (bj == 0) { q0 = *(const f32x4*)(bp + (ro + HALF) * 4 + l4); q1 = *(const f32x4*)(bp + (ro + HALF) * 4 + l4 + 16); }
;                 else if (g + 1 < 8) { q0 = *(const f32x4*)(bp + (size_t)rn * ldc * 4 + l4); q1 = *(const f32x4*)(bp + (size_t)rn * ldc * 4 + l4 + 16); }
;                 const f32x4 z0 = gv[bj][0] * ((p0 - mu) * r) + acc[ai][bj][m][0] + cv[bj][0], z1 = gv[bj][1] * ((p1 - mu) * r) + acc[ai][bj][m][1] + cv[bj][1];
;                 *(f32x4*)(op + ro * 4 + l4) = z0; *(f32x4*)(op + ro * 4 + l4 + 16) = z1;
;                 s1 += ((z0[0] + z0[1]) + (z0[2] + z0[3])) + ((z1[0] + z1[1]) + (z1[2] + z1[3]));
;                 s2 += ((z0[0] * z0[0] + z0[1] * z0[1]) + (z0[2] * z0[2] + z0[3] * z0[3])) + ((z1[0] * z1[0] + z1[1] * z1[1]) + (z1[2] * z1[2] + z1[3] * z1[3]));
;                 if (zb) { u32x4 w; w.x = cvt_pk_bf16(z0[0], z0[1]); w.y = cvt_pk_bf16(z0[2], z0[3]); w.z = cvt_pk_bf16(z1[0], z1[1]); w.w = cvt_pk_bf16(z1[2], z1[3]); *(u32x4*)(zp + ro * 2 + l2) = w; }
;                 p0 = q0; p1 = q1; }
.LBB0_986:
	s_or_b64 exec, exec, s[24:25]
	s_mov_b64 s[4:5], 0x20200
	v_lshl_add_u64 v[98:99], v[206:207], 0, s[4:5]
	s_mov_b32 s4, 0x20000
	s_waitcnt lgkmcnt(1)
	v_add_co_u32_e32 v100, vcc, s4, v206
	global_load_dwordx2 v[122:123], v[212:213], off offset:384
	s_waitcnt lgkmcnt(0)
	v_addc_co_u32_e32 v101, vcc, 0, v207, vcc
	global_load_dwordx4 v[114:117], v[100:101], off offset:512
	global_load_dwordx4 v[110:113], v[98:99], off offset:16
	v_pk_mul_f32 v[126:127], v[150:151], s[54:55] op_sel_hi:[1,0]
	s_nop 0
	v_fma_f32 v98, -v126, v126, v127
	v_add_f32_e32 v98, 0x3727c5ac, v98
	v_rsq_f32_e32 v124, v98
	s_waitcnt vmcnt(6)
	v_sub_f32_e32 v99, v119, v126
	v_sub_f32_e32 v98, v118, v126
	v_sub_f32_e32 v101, v121, v126
	v_pk_mul_f32 v[98:99], v[124:125], v[98:99] op_sel_hi:[0,1]
	v_sub_f32_e32 v100, v120, v126
	v_pk_fma_f32 v[94:95], v[202:203], v[98:99], v[94:95]
	s_waitcnt vmcnt(5)
	v_sub_f32_e32 v99, v107, v126
	v_sub_f32_e32 v98, v106, v126
	v_pk_mul_f32 v[100:101], v[124:125], v[100:101] op_sel_hi:[0,1]
	v_pk_mul_f32 v[98:99], v[124:125], v[98:99] op_sel_hi:[0,1]
	v_pk_fma_f32 v[96:97], v[196:197], v[100:101], v[96:97]
	v_sub_f32_e32 v101, v109, v126
	v_sub_f32_e32 v100, v108, v126
	v_pk_fma_f32 v[90:91], v[194:195], v[98:99], v[90:91]
	v_pk_mul_f32 v[100:101], v[124:125], v[100:101] op_sel_hi:[0,1]
	v_pk_add_f32 v[102:103], v[190:191], v[90:91]
	v_add_co_u32_e32 v90, vcc, 0x20000, v206
	v_pk_fma_f32 v[92:93], v[192:193], v[100:101], v[92:93]
	s_nop 0
	v_addc_co_u32_e32 v91, vcc, 0, v207, vcc
	v_pk_add_f32 v[96:97], v[198:199], v[96:97]
	v_pk_add_f32 v[94:95], v[200:201], v[94:95]
	v_pk_add_f32 v[104:105], v[188:189], v[92:93]
	s_and_b64 vcc, exec, s[42:43]
	global_store_dwordx4 v[130:131], v[94:97], off nt
	global_store_dwordx4 v[90:91], v[102:105], off offset:16 nt
	s_cbranch_vccnz .LBB0_988
	v_add_co_u32_e32 v98, vcc, 0x10000, v204
	v_cvt_pk_bf16_f32 v90, v94, v95
	v_cvt_pk_bf16_f32 v91, v96, v97
	v_cvt_pk_bf16_f32 v92, v102, v103
	v_cvt_pk_bf16_f32 v93, v104, v105
	s_nop 1
	v_addc_co_u32_e32 v99, vcc, 0, v205, vcc
	global_store_dwordx4 v[98:99], v[90:93], off
.LBB0_988:
	s_nop 1
	v_add_co_u32_e32 v90, vcc, 0x30000, v206
	s_mov_b64 s[4:5], 0x30000
	s_nop 0
	v_addc_co_u32_e32 v91, vcc, 0, v207, vcc
	v_lshl_add_u64 v[108:109], v[206:207], 0, s[4:5]
	global_load_dwordx4 v[98:101], v[90:91], off
	s_nop 0
	global_load_dwordx4 v[90:93], v[108:109], off offset:16
	v_mov_b32_e32 v125, v124
	s_waitcnt vmcnt(5)
	v_sub_f32_e32 v107, v115, v126
	v_sub_f32_e32 v106, v114, v126
	v_pk_mul_f32 v[106:107], v[124:125], v[106:107]
	v_sub_f32_e32 v115, v117, v126
	v_pk_fma_f32 v[86:87], v[210:211], v[106:107], v[86:87]
	s_waitcnt vmcnt(4)
	v_sub_f32_e32 v107, v111, v126
	v_sub_f32_e32 v106, v110, v126
	v_sub_f32_e32 v114, v116, v126
	v_mov_b32_e32 v116, v124
	v_mov_b32_e32 v117, v124
	v_sub_f32_e32 v111, v113, v126
	v_sub_f32_e32 v110, v112, v126
	v_pk_mul_f32 v[106:107], v[124:125], v[106:107]
	v_pk_mul_f32 v[114:115], v[116:117], v[114:115]
	v_pk_mul_f32 v[110:111], v[116:117], v[110:111]
	v_pk_fma_f32 v[82:83], v[144:145], v[106:107], v[82:83]
	v_add_co_u32_e32 v106, vcc, 0x20000, v206
	v_pk_fma_f32 v[88:89], v[208:209], v[114:115], v[88:89]
	v_pk_fma_f32 v[84:85], v[142:143], v[110:111], v[84:85]
	v_addc_co_u32_e32 v107, vcc, 0, v207, vcc
	v_pk_add_f32 v[88:89], v[146:147], v[88:89]
	v_pk_add_f32 v[86:87], v[148:149], v[86:87]
	v_pk_add_f32 v[84:85], v[140:141], v[84:85]
	v_pk_add_f32 v[82:83], v[138:139], v[82:83]
	s_and_b64 vcc, exec, s[42:43]
	global_store_dwordx4 v[106:107], v[86:89], off offset:512 nt
	global_store_dwordx4 v[106:107], v[82:85], off offset:528 nt
	s_cbranch_vccnz .LBB0_990
	v_add_co_u32_e32 v106, vcc, 0x10000, v204
	v_cvt_pk_bf16_f32 v110, v86, v87
	v_cvt_pk_bf16_f32 v111, v88, v89
	v_cvt_pk_bf16_f32 v112, v82, v83
	v_cvt_pk_bf16_f32 v113, v84, v85
	s_nop 1
	v_addc_co_u32_e32 v107, vcc, 0, v205, vcc
	global_store_dwordx4 v[106:107], v[110:113], off offset:256

; __device__ __forceinline__ unsigned cvt_pk_bf16(float lo, float hi) { unsigned r; asm volatile("v_cvt_pk_bf16_f32 %0, %1, %2" : "=v"(r) : "v"(lo), "v"(hi)); return r; }
; __device__ __forceinline__ void stats_mr(const f32x2 s, float& mu, float& r) { mu = s.x * (1.0f / 1024.0f); const float var = s.y * (1.0f / 1024.0f) - mu * mu; r = __builtin_amdgcn_rsqf(var + 1e-5f); }
;     __device__ __forceinline__ void operator()(const f32x4 (&acc)[2][2][4][2], const Unit& u, int wr, int wc, int fr, int fq) const {
;     ...
;         for (int g = 0; g < 8; ++g) { const int ai = g >> 2, m = g & 3; const int rr = ai * HALF + m * 16, rn = ((g + 1) >> 2) * HALF + ((g + 1) & 3) * 16;
;             f32x2 sv_n = sv_c; if (g + 1 < 8) sv_n = *(const f32x2*)(sp + (size_t)rn * 8 + ls);
;             float mu, r; stats_mr(sv_c, mu, r); float s1 = 0.f, s2 = 0.f;
; #pragma unroll
;             for (int bj = 0; bj < 2; ++bj) { const size_t ro = (size_t)rr * ldc + bj * HALF;
;                 f32x4 q0 = p0, q1 = p1;
;                 if (bj == 0) { q0 = *(const f32x4*)(bp + (ro + HALF) * 4 + l4); q1 = *(const f32x4*)(bp + (ro + HALF) * 4 + l4 + 16); }
;                 else if (g + 1 < 8) { q0 = *(const f32x4*)(bp + (size_t)rn * ldc * 4 + l4); q1 = *(const f32x4*)(bp + (size_t)rn * ldc * 4 + l4 + 16); }
;                 const f32x4 z0 = gv[bj][0] * ((p0 - mu) * r) + acc[ai][bj][m][0] + cv[bj][0], z1 = gv[bj][1] * ((p1 - mu) * r) + acc[ai][bj][m][1] + cv[bj][1];
;                 *(f32x4*)(op + ro * 4 + l4) = z0; *(f32x4*)(op + ro * 4 + l4 + 16) = z1;
;                 s1 += ((z0[0] + z0[1]) + (z0[2] + z0[3])) + ((z1[0] + z1[1]) + (z1[2] + z1[3]));
;                 s2 += ((z0[0] * z0[0] + z0[1] * z0[1]) + (z0[2] * z0[2] + z0[3] * z0[3])) + ((z1[0] * z1[0] + z1[1] * z1[1]) + (z1[2] * z1[2] + z1[3] * z1[3]));
;                 if (zb) { u32x4 w; w.x = cvt_pk_bf16(z0[0], z0[1]); w.y = cvt_pk_bf16(z0[2], z0[3]); w.z = cvt_pk_bf16(z1[0], z1[1]); w.w = cvt_pk_bf16(z1[2], z1[3]); *(u32x4*)(zp + ro * 2 + l2) = w; }
;                 p0 = q0; p1 = q1; }
.LBB0_992:
	s_or_b64 exec, exec, s[24:25]
	s_mov_b64 s[4:5], 0x30200
	v_lshl_add_u64 v[82:83], v[206:207], 0, s[4:5]
	s_mov_b32 s4, 0x30000
	s_waitcnt lgkmcnt(1)
	v_add_co_u32_e32 v84, vcc, s4, v206
	global_load_dwordx2 v[106:107], v[212:213], off offset:1024
	s_waitcnt lgkmcnt(0)
	v_addc_co_u32_e32 v85, vcc, 0, v207, vcc
	global_load_dwordx4 v[102:105], v[84:85], off offset:512
	global_load_dwordx4 v[94:97], v[82:83], off offset:16
	v_pk_mul_f32 v[112:113], v[122:123], s[54:55] op_sel_hi:[1,0]
	s_nop 0
	v_fma_f32 v82, -v112, v112, v113
	v_add_f32_e32 v82, 0x3727c5ac, v82
	v_rsq_f32_e32 v110, v82
	s_waitcnt vmcnt(6)
	v_sub_f32_e32 v83, v99, v112
	v_sub_f32_e32 v82, v98, v112
	v_sub_f32_e32 v85, v101, v112
	v_pk_mul_f32 v[82:83], v[110:111], v[82:83] op_sel_hi:[0,1]
	v_sub_f32_e32 v84, v100, v112
	v_pk_fma_f32 v[78:79], v[202:203], v[82:83], v[78:79]
	s_waitcnt vmcnt(5)
	v_sub_f32_e32 v83, v91, v112
	v_sub_f32_e32 v82, v90, v112
	v_pk_mul_f32 v[84:85], v[110:111], v[84:85] op_sel_hi:[0,1]
	v_pk_mul_f32 v[82:83], v[110:111], v[82:83] op_sel_hi:[0,1]
	v_pk_fma_f32 v[80:81], v[196:197], v[84:85], v[80:81]
	v_sub_f32_e32 v85, v93, v112
	v_sub_f32_e32 v84, v92, v112
	v_pk_fma_f32 v[74:75], v[194:195], v[82:83], v[74:75]
	v_pk_mul_f32 v[84:85], v[110:111], v[84:85] op_sel_hi:[0,1]
	v_pk_add_f32 v[86:87], v[190:191], v[74:75]
	v_add_co_u32_e32 v74, vcc, 0x30000, v206
	v_pk_fma_f32 v[76:77], v[192:193], v[84:85], v[76:77]
	s_nop 0
	v_addc_co_u32_e32 v75, vcc, 0, v207, vcc
	v_pk_add_f32 v[80:81], v[198:199], v[80:81]
	v_pk_add_f32 v[78:79], v[200:201], v[78:79]
	v_pk_add_f32 v[88:89], v[188:189], v[76:77]
	s_and_b64 vcc, exec, s[42:43]
	global_store_dwordx4 v[108:109], v[78:81], off nt
	global_store_dwordx4 v[74:75], v[86:89], off offset:16 nt
	s_cbranch_vccnz .LBB0_994
	v_add_co_u32_e32 v82, vcc, 0x18000, v204
	v_cvt_pk_bf16_f32 v74, v78, v79
	v_cvt_pk_bf16_f32 v75, v80, v81
	v_cvt_pk_bf16_f32 v76, v86, v87
	v_cvt_pk_bf16_f32 v77, v88, v89
	s_nop 1
	v_addc_co_u32_e32 v83, vcc, 0, v205, vcc
	global_store_dwordx4 v[82:83], v[74:77], off
.LBB0_994:
	s_nop 1
	v_add_co_u32_e32 v74, vcc, 0x80000, v206
	s_mov_b64 s[4:5], 0x80000
	s_nop 0
	v_addc_co_u32_e32 v75, vcc, 0, v207, vcc
	v_lshl_add_u64 v[92:93], v[206:207], 0, s[4:5]
	global_load_dwordx4 v[82:85], v[74:75], off
	s_nop 0
	global_load_dwordx4 v[74:77], v[92:93], off offset:16
	v_mov_b32_e32 v111, v110
	s_waitcnt vmcnt(5)
	v_sub_f32_e32 v91, v103, v112
	v_sub_f32_e32 v90, v102, v112
	v_pk_mul_f32 v[90:91], v[110:111], v[90:91]
	v_sub_f32_e32 v99, v105, v112
	v_pk_fma_f32 v[70:71], v[210:211], v[90:91], v[70:71]
	s_waitcnt vmcnt(4)
	v_sub_f32_e32 v91, v95, v112
	v_sub_f32_e32 v90, v94, v112
	v_sub_f32_e32 v98, v104, v112
	v_mov_b32_e32 v100, v110
	v_mov_b32_e32 v101, v110
	v_sub_f32_e32 v95, v97, v112
	v_sub_f32_e32 v94, v96, v112
	v_pk_mul_f32 v[90:91], v[110:111], v[90:91]
	v_pk_mul_f32 v[98:99], v[100:101], v[98:99]
	v_pk_mul_f32 v[94:95], v[100:101], v[94:95]
	v_pk_fma_f32 v[66:67], v[144:145], v[90:91], v[66:67]
	v_add_co_u32_e32 v90, vcc, 0x30000, v206
	v_pk_fma_f32 v[72:73], v[208:209], v[98:99], v[72:73]
	v_pk_fma_f32 v[68:69], v[142:143], v[94:95], v[68:69]
	v_addc_co_u32_e32 v91, vcc, 0, v207, vcc
	v_pk_add_f32 v[72:73], v[146:147], v[72:73]
	v_pk_add_f32 v[70:71], v[148:149], v[70:71]
	v_pk_add_f32 v[68:69], v[140:141], v[68:69]
	v_pk_add_f32 v[66:67], v[138:139], v[66:67]
	s_and_b64 vcc, exec, s[42:43]
	global_store_dwordx4 v[90:91], v[70:73], off offset:512 nt
	global_store_dwordx4 v[90:91], v[66:69], off offset:528 nt
	s_cbranch_vccnz .LBB0_996
	v_add_co_u32_e32 v90, vcc, 0x18000, v204
	v_cvt_pk_bf16_f32 v94, v70, v71
	v_cvt_pk_bf16_f32 v95, v72, v73
	v_cvt_pk_bf16_f32 v96, v66, v67
	v_cvt_pk_bf16_f32 v97, v68, v69
	s_nop 1
	v_addc_co_u32_e32 v91, vcc, 0, v205, vcc
	global_store_dwordx4 v[90:91], v[94:97], off offset:256

; __device__ __forceinline__ unsigned cvt_pk_bf16(float lo, float hi) { unsigned r; asm volatile("v_cvt_pk_bf16_f32 %0, %1, %2" : "=v"(r) : "v"(lo), "v"(hi)); return r; }
; __device__ __forceinline__ void stats_mr(const f32x2 s, float& mu, float& r) { mu = s.x * (1.0f / 1024.0f); const float var = s.y * (1.0f / 1024.0f) - mu * mu; r = __builtin_amdgcn_rsqf(var + 1e-5f); }
;     __device__ __forceinline__ void operator()(const f32x4 (&acc)[2][2][4][2], const Unit& u, int wr, int wc, int fr, int fq) const {
;     ...
;         for (int g = 0; g < 8; ++g) { const int ai = g >> 2, m = g & 3; const int rr = ai * HALF + m * 16, rn = ((g + 1) >> 2) * HALF + ((g + 1) & 3) * 16;
;             f32x2 sv_n = sv_c; if (g + 1 < 8) sv_n = *(const f32x2*)(sp + (size_t)rn * 8 + ls);
;             float mu, r; stats_mr(sv_c, mu, r); float s1 = 0.f, s2 = 0.f;
; #pragma unroll
;             for (int bj = 0; bj < 2; ++bj) { const size_t ro = (size_t)rr * ldc + bj * HALF;
;                 f32x4 q0 = p0, q1 = p1;
;                 if (bj == 0) { q0 = *(const f32x4*)(bp + (ro + HALF) * 4 + l4); q1 = *(const f32x4*)(bp + (ro + HALF) * 4 + l4 + 16); }
;                 else if (g + 1 < 8) { q0 = *(const f32x4*)(bp + (size_t)rn * ldc * 4 + l4); q1 = *(const f32x4*)(bp + (size_t)rn * ldc * 4 + l4 + 16); }
;                 const f32x4 z0 = gv[bj][0] * ((p0 - mu) * r) + acc[ai][bj][m][0] + cv[bj][0], z1 = gv[bj][1] * ((p1 - mu) * r) + acc[ai][bj][m][1] + cv[bj][1];
;                 *(f32x4*)(op + ro * 4 + l4) = z0; *(f32x4*)(op + ro * 4 + l4 + 16) = z1;
;                 s1 += ((z0[0] + z0[1]) + (z0[2] + z0[3])) + ((z1[0] + z1[1]) + (z1[2] + z1[3]));
;                 s2 += ((z0[0] * z0[0] + z0[1] * z0[1]) + (z0[2] * z0[2] + z0[3] * z0[3])) + ((z1[0] * z1[0] + z1[1] * z1[1]) + (z1[2] * z1[2] + z1[3] * z1[3]));
;                 if (zb) { u32x4 w; w.x = cvt_pk_bf16(z0[0], z0[1]); w.y = cvt_pk_bf16(z0[2], z0[3]); w.z = cvt_pk_bf16(z1[0], z1[1]); w.w = cvt_pk_bf16(z1[2], z1[3]); *(u32x4*)(zp + ro * 2 + l2) = w; }
;                 p0 = q0; p1 = q1; }
.LBB0_998:
	s_or_b64 exec, exec, s[24:25]
	s_mov_b64 s[4:5], 0x80200
	v_lshl_add_u64 v[66:67], v[206:207], 0, s[4:5]
	s_mov_b32 s4, 0x80000
	s_waitcnt lgkmcnt(1)
	v_add_co_u32_e32 v68, vcc, s4, v206
	global_load_dwordx2 v[90:91], v[212:213], off offset:1152
	s_waitcnt lgkmcnt(0)
	v_addc_co_u32_e32 v69, vcc, 0, v207, vcc
	global_load_dwordx4 v[86:89], v[68:69], off offset:512
	global_load_dwordx4 v[78:81], v[66:67], off offset:16
	v_pk_mul_f32 v[96:97], v[106:107], s[54:55] op_sel_hi:[1,0]
	s_nop 0
	v_fma_f32 v66, -v96, v96, v97
	v_add_f32_e32 v66, 0x3727c5ac, v66
	v_rsq_f32_e32 v94, v66
	s_waitcnt vmcnt(6)
	v_sub_f32_e32 v67, v83, v96
	v_sub_f32_e32 v66, v82, v96
	v_sub_f32_e32 v69, v85, v96
	v_pk_mul_f32 v[66:67], v[94:95], v[66:67] op_sel_hi:[0,1]
	v_sub_f32_e32 v68, v84, v96
	v_pk_fma_f32 v[62:63], v[202:203], v[66:67], v[62:63]
	s_waitcnt vmcnt(5)
	v_sub_f32_e32 v67, v75, v96
	v_sub_f32_e32 v66, v74, v96
	v_pk_mul_f32 v[68:69], v[94:95], v[68:69] op_sel_hi:[0,1]
	v_pk_mul_f32 v[66:67], v[94:95], v[66:67] op_sel_hi:[0,1]
	v_pk_fma_f32 v[64:65], v[196:197], v[68:69], v[64:65]
	v_sub_f32_e32 v69, v77, v96
	v_sub_f32_e32 v68, v76, v96
	v_pk_fma_f32 v[58:59], v[194:195], v[66:67], v[58:59]
	v_pk_mul_f32 v[68:69], v[94:95], v[68:69] op_sel_hi:[0,1]
	v_pk_add_f32 v[70:71], v[190:191], v[58:59]
	v_add_co_u32_e32 v58, vcc, 0x80000, v206
	v_pk_fma_f32 v[60:61], v[192:193], v[68:69], v[60:61]
	s_nop 0
	v_addc_co_u32_e32 v59, vcc, 0, v207, vcc
	v_pk_add_f32 v[64:65], v[198:199], v[64:65]
	v_pk_add_f32 v[62:63], v[200:201], v[62:63]
	v_pk_add_f32 v[72:73], v[188:189], v[60:61]
	s_and_b64 vcc, exec, s[42:43]
	global_store_dwordx4 v[92:93], v[62:65], off nt
	global_store_dwordx4 v[58:59], v[70:73], off offset:16 nt
	s_cbranch_vccnz .LBB0_1000
	v_add_co_u32_e32 v66, vcc, 0x40000, v204
	v_cvt_pk_bf16_f32 v58, v62, v63
	v_cvt_pk_bf16_f32 v59, v64, v65
	v_cvt_pk_bf16_f32 v60, v70, v71
	v_cvt_pk_bf16_f32 v61, v72, v73
	s_nop 1
	v_addc_co_u32_e32 v67, vcc, 0, v205, vcc
	global_store_dwordx4 v[66:67], v[58:61], off
.LBB0_1000:
	s_nop 1
	v_add_co_u32_e32 v58, vcc, 0x90000, v206
	v_lshl_add_u64 v[76:77], v[206:207], 0, s[28:29]
	s_nop 0
	v_addc_co_u32_e32 v59, vcc, 0, v207, vcc
	global_load_dwordx4 v[66:69], v[58:59], off
	s_nop 0
	global_load_dwordx4 v[58:61], v[76:77], off offset:16
	v_mov_b32_e32 v95, v94
	s_waitcnt vmcnt(5)
	v_sub_f32_e32 v75, v87, v96
	v_sub_f32_e32 v74, v86, v96
	v_pk_mul_f32 v[74:75], v[94:95], v[74:75]
	v_sub_f32_e32 v83, v89, v96
	v_pk_fma_f32 v[54:55], v[210:211], v[74:75], v[54:55]
	s_waitcnt vmcnt(4)
	v_sub_f32_e32 v75, v79, v96
	v_sub_f32_e32 v74, v78, v96
	v_sub_f32_e32 v82, v88, v96
	v_mov_b32_e32 v84, v94
	v_mov_b32_e32 v85, v94
	v_sub_f32_e32 v79, v81, v96
	v_sub_f32_e32 v78, v80, v96
	v_pk_mul_f32 v[74:75], v[94:95], v[74:75]
	v_pk_mul_f32 v[82:83], v[84:85], v[82:83]
	v_pk_mul_f32 v[78:79], v[84:85], v[78:79]
	v_pk_fma_f32 v[50:51], v[144:145], v[74:75], v[50:51]
	v_add_co_u32_e32 v74, vcc, 0x80000, v206
	v_pk_fma_f32 v[56:57], v[208:209], v[82:83], v[56:57]
	v_pk_fma_f32 v[52:53], v[142:143], v[78:79], v[52:53]
	v_addc_co_u32_e32 v75, vcc, 0, v207, vcc
	v_pk_add_f32 v[56:57], v[146:147], v[56:57]
	v_pk_add_f32 v[54:55], v[148:149], v[54:55]
	v_pk_add_f32 v[52:53], v[140:141], v[52:53]
	v_pk_add_f32 v[50:51], v[138:139], v[50:51]
	s_and_b64 vcc, exec, s[42:43]
	global_store_dwordx4 v[74:75], v[54:57], off offset:512 nt
	global_store_dwordx4 v[74:75], v[50:53], off offset:528 nt
	s_cbranch_vccnz .LBB0_1002
	v_add_co_u32_e32 v74, vcc, 0x40000, v204
	v_cvt_pk_bf16_f32 v78, v54, v55
	v_cvt_pk_bf16_f32 v79, v56, v57
	v_cvt_pk_bf16_f32 v80, v50, v51
	v_cvt_pk_bf16_f32 v81, v52, v53
	s_nop 1
	v_addc_co_u32_e32 v75, vcc, 0, v205, vcc
	global_store_dwordx4 v[74:75], v[78:81], off offset:256

; __device__ __forceinline__ unsigned cvt_pk_bf16(float lo, float hi) { unsigned r; asm volatile("v_cvt_pk_bf16_f32 %0, %1, %2" : "=v"(r) : "v"(lo), "v"(hi)); return r; }
; __device__ __forceinline__ void stats_mr(const f32x2 s, float& mu, float& r) { mu = s.x * (1.0f / 1024.0f); const float var = s.y * (1.0f / 1024.0f) - mu * mu; r = __builtin_amdgcn_rsqf(var + 1e-5f); }
;     __device__ __forceinline__ void operator()(const f32x4 (&acc)[2][2][4][2], const Unit& u, int wr, int wc, int fr, int fq) const {
;     ...
;         for (int g = 0; g < 8; ++g) { const int ai = g >> 2, m = g & 3; const int rr = ai * HALF + m * 16, rn = ((g + 1) >> 2) * HALF + ((g + 1) & 3) * 16;
;             f32x2 sv_n = sv_c; if (g + 1 < 8) sv_n = *(const f32x2*)(sp + (size_t)rn * 8 + ls);
;             float mu, r; stats_mr(sv_c, mu, r); float s1 = 0.f, s2 = 0.f;
; #pragma unroll
;             for (int bj = 0; bj < 2; ++bj) { const size_t ro = (size_t)rr * ldc + bj * HALF;
;                 f32x4 q0 = p0, q1 = p1;
;                 if (bj == 0) { q0 = *(const f32x4*)(bp + (ro + HALF) * 4 + l4); q1 = *(const f32x4*)(bp + (ro + HALF) * 4 + l4 + 16); }
;                 else if (g + 1 < 8) { q0 = *(const f32x4*)(bp + (size_t)rn * ldc * 4 + l4); q1 = *(const f32x4*)(bp + (size_t)rn * ldc * 4 + l4 + 16); }
;                 const f32x4 z0 = gv[bj][0] * ((p0 - mu) * r) + acc[ai][bj][m][0] + cv[bj][0], z1 = gv[bj][1] * ((p1 - mu) * r) + acc[ai][bj][m][1] + cv[bj][1];
;                 *(f32x4*)(op + ro * 4 + l4) = z0; *(f32x4*)(op + ro * 4 + l4 + 16) = z1;
;                 s1 += ((z0[0] + z0[1]) + (z0[2] + z0[3])) + ((z1[0] + z1[1]) + (z1[2] + z1[3]));
;                 s2 += ((z0[0] * z0[0] + z0[1] * z0[1]) + (z0[2] * z0[2] + z0[3] * z0[3])) + ((z1[0] * z1[0] + z1[1] * z1[1]) + (z1[2] * z1[2] + z1[3] * z1[3]));
;                 if (zb) { u32x4 w; w.x = cvt_pk_bf16(z0[0], z0[1]); w.y = cvt_pk_bf16(z0[2], z0[3]); w.z = cvt_pk_bf16(z1[0], z1[1]); w.w = cvt_pk_bf16(z1[2], z1[3]); *(u32x4*)(zp + ro * 2 + l2) = w; }
;                 p0 = q0; p1 = q1; }
.LBB0_1004:
	s_or_b64 exec, exec, s[24:25]
	s_waitcnt lgkmcnt(1)
	v_add_co_u32_e32 v52, vcc, s79, v206
	s_mov_b64 s[4:5], 0x90200
	s_waitcnt lgkmcnt(0)
	v_addc_co_u32_e32 v53, vcc, 0, v207, vcc
	global_load_dwordx2 v[74:75], v[212:213], off offset:1280
	v_lshl_add_u64 v[50:51], v[206:207], 0, s[4:5]
	global_load_dwordx4 v[70:73], v[52:53], off offset:512
	global_load_dwordx4 v[62:65], v[50:51], off offset:16
	v_pk_mul_f32 v[80:81], v[90:91], s[54:55] op_sel_hi:[1,0]
	s_nop 0
	v_fma_f32 v50, -v80, v80, v81
	v_add_f32_e32 v50, 0x3727c5ac, v50
	v_rsq_f32_e32 v78, v50
	s_waitcnt vmcnt(6)
	v_sub_f32_e32 v51, v67, v80
	v_sub_f32_e32 v50, v66, v80
	v_sub_f32_e32 v53, v69, v80
	v_pk_mul_f32 v[50:51], v[78:79], v[50:51] op_sel_hi:[0,1]
	v_sub_f32_e32 v52, v68, v80
	v_pk_fma_f32 v[46:47], v[202:203], v[50:51], v[46:47]
	s_waitcnt vmcnt(5)
	v_sub_f32_e32 v51, v59, v80
	v_sub_f32_e32 v50, v58, v80
	v_pk_mul_f32 v[52:53], v[78:79], v[52:53] op_sel_hi:[0,1]
	v_pk_mul_f32 v[50:51], v[78:79], v[50:51] op_sel_hi:[0,1]
	v_pk_fma_f32 v[48:49], v[196:197], v[52:53], v[48:49]
	v_sub_f32_e32 v53, v61, v80
	v_sub_f32_e32 v52, v60, v80
	v_pk_fma_f32 v[42:43], v[194:195], v[50:51], v[42:43]
	v_pk_mul_f32 v[52:53], v[78:79], v[52:53] op_sel_hi:[0,1]
	v_pk_add_f32 v[54:55], v[190:191], v[42:43]
	v_add_co_u32_e32 v42, vcc, 0x90000, v206
	v_pk_fma_f32 v[44:45], v[192:193], v[52:53], v[44:45]
	s_nop 0
	v_addc_co_u32_e32 v43, vcc, 0, v207, vcc
	v_pk_add_f32 v[48:49], v[198:199], v[48:49]
	v_pk_add_f32 v[46:47], v[200:201], v[46:47]
	v_pk_add_f32 v[56:57], v[188:189], v[44:45]
	s_and_b64 vcc, exec, s[42:43]
	global_store_dwordx4 v[76:77], v[46:49], off nt
	global_store_dwordx4 v[42:43], v[54:57], off offset:16 nt
	s_cbranch_vccnz .LBB0_1006
	v_add_co_u32_e32 v50, vcc, 0x48000, v204
	v_cvt_pk_bf16_f32 v42, v46, v47
	v_cvt_pk_bf16_f32 v43, v48, v49
	v_cvt_pk_bf16_f32 v44, v54, v55
	v_cvt_pk_bf16_f32 v45, v56, v57
	s_nop 1
	v_addc_co_u32_e32 v51, vcc, 0, v205, vcc
	global_store_dwordx4 v[50:51], v[42:45], off
.LBB0_1006:
	s_nop 1
	v_add_co_u32_e32 v42, vcc, 0xa0000, v206
	s_mov_b64 s[4:5], 0xa0000
	s_nop 0
	v_addc_co_u32_e32 v43, vcc, 0, v207, vcc
	v_lshl_add_u64 v[60:61], v[206:207], 0, s[4:5]
	global_load_dwordx4 v[50:53], v[42:43], off
	s_nop 0
	global_load_dwordx4 v[42:45], v[60:61], off offset:16
	v_mov_b32_e32 v79, v78
	s_waitcnt vmcnt(5)
	v_sub_f32_e32 v59, v71, v80
	v_sub_f32_e32 v58, v70, v80
	v_pk_mul_f32 v[58:59], v[78:79], v[58:59]
	v_sub_f32_e32 v67, v73, v80
	v_pk_fma_f32 v[38:39], v[210:211], v[58:59], v[38:39]
	s_waitcnt vmcnt(4)
	v_sub_f32_e32 v59, v63, v80
	v_sub_f32_e32 v58, v62, v80
	v_sub_f32_e32 v66, v72, v80
	v_mov_b32_e32 v68, v78
	v_mov_b32_e32 v69, v78
	v_sub_f32_e32 v63, v65, v80
	v_sub_f32_e32 v62, v64, v80
	v_pk_mul_f32 v[58:59], v[78:79], v[58:59]
	v_pk_mul_f32 v[66:67], v[68:69], v[66:67]
	v_pk_mul_f32 v[62:63], v[68:69], v[62:63]
	v_pk_fma_f32 v[34:35], v[144:145], v[58:59], v[34:35]
	v_add_co_u32_e32 v58, vcc, 0x90000, v206
	v_pk_fma_f32 v[40:41], v[208:209], v[66:67], v[40:41]
	v_pk_fma_f32 v[36:37], v[142:143], v[62:63], v[36:37]
	v_addc_co_u32_e32 v59, vcc, 0, v207, vcc
	v_pk_add_f32 v[40:41], v[146:147], v[40:41]
	v_pk_add_f32 v[38:39], v[148:149], v[38:39]
	v_pk_add_f32 v[36:37], v[140:141], v[36:37]
	v_pk_add_f32 v[34:35], v[138:139], v[34:35]
	s_and_b64 vcc, exec, s[42:43]
	global_store_dwordx4 v[58:59], v[38:41], off offset:512 nt
	global_store_dwordx4 v[58:59], v[34:37], off offset:528 nt
	s_cbranch_vccnz .LBB0_1008
	v_add_co_u32_e32 v58, vcc, 0x48000, v204
	v_cvt_pk_bf16_f32 v62, v38, v39
	v_cvt_pk_bf16_f32 v63, v40, v41
	v_cvt_pk_bf16_f32 v64, v34, v35
	v_cvt_pk_bf16_f32 v65, v36, v37
	s_nop 1
	v_addc_co_u32_e32 v59, vcc, 0, v205, vcc
	global_store_dwordx4 v[58:59], v[62:65], off offset:256

; __device__ __forceinline__ unsigned cvt_pk_bf16(float lo, float hi) { unsigned r; asm volatile("v_cvt_pk_bf16_f32 %0, %1, %2" : "=v"(r) : "v"(lo), "v"(hi)); return r; }
; __device__ __forceinline__ void stats_mr(const f32x2 s, float& mu, float& r) { mu = s.x * (1.0f / 1024.0f); const float var = s.y * (1.0f / 1024.0f) - mu * mu; r = __builtin_amdgcn_rsqf(var + 1e-5f); }
;     __device__ __forceinline__ void operator()(const f32x4 (&acc)[2][2][4][2], const Unit& u, int wr, int wc, int fr, int fq) const {
;     ...
;         for (int g = 0; g < 8; ++g) { const int ai = g >> 2, m = g & 3; const int rr = ai * HALF + m * 16, rn = ((g + 1) >> 2) * HALF + ((g + 1) & 3) * 16;
;             f32x2 sv_n = sv_c; if (g + 1 < 8) sv_n = *(const f32x2*)(sp + (size_t)rn * 8 + ls);
;             float mu, r; stats_mr(sv_c, mu, r); float s1 = 0.f, s2 = 0.f;
; #pragma unroll
;             for (int bj = 0; bj < 2; ++bj) { const size_t ro = (size_t)rr * ldc + bj * HALF;
;                 f32x4 q0 = p0, q1 = p1;
;                 if (bj == 0) { q0 = *(const f32x4*)(bp + (ro + HALF) * 4 + l4); q1 = *(const f32x4*)(bp + (ro + HALF) * 4 + l4 + 16); }
;                 else if (g + 1 < 8) { q0 = *(const f32x4*)(bp + (size_t)rn * ldc * 4 + l4); q1 = *(const f32x4*)(bp + (size_t)rn * ldc * 4 + l4 + 16); }
;                 const f32x4 z0 = gv[bj][0] * ((p0 - mu) * r) + acc[ai][bj][m][0] + cv[bj][0], z1 = gv[bj][1] * ((p1 - mu) * r) + acc[ai][bj][m][1] + cv[bj][1];
;                 *(f32x4*)(op + ro * 4 + l4) = z0; *(f32x4*)(op + ro * 4 + l4 + 16) = z1;
;                 s1 += ((z0[0] + z0[1]) + (z0[2] + z0[3])) + ((z1[0] + z1[1]) + (z1[2] + z1[3]));
;                 s2 += ((z0[0] * z0[0] + z0[1] * z0[1]) + (z0[2] * z0[2] + z0[3] * z0[3])) + ((z1[0] * z1[0] + z1[1] * z1[1]) + (z1[2] * z1[2] + z1[3] * z1[3]));
;                 if (zb) { u32x4 w; w.x = cvt_pk_bf16(z0[0], z0[1]); w.y = cvt_pk_bf16(z0[2], z0[3]); w.z = cvt_pk_bf16(z1[0], z1[1]); w.w = cvt_pk_bf16(z1[2], z1[3]); *(u32x4*)(zp + ro * 2 + l2) = w; }
;                 p0 = q0; p1 = q1; }
.LBB0_1010:
	s_or_b64 exec, exec, s[24:25]
	s_mov_b64 s[4:5], 0xa0200
	v_lshl_add_u64 v[34:35], v[206:207], 0, s[4:5]
	s_mov_b32 s4, 0xa0000
	s_waitcnt lgkmcnt(1)
	v_add_co_u32_e32 v36, vcc, s4, v206
	global_load_dwordx2 v[58:59], v[212:213], off offset:1408
	s_waitcnt lgkmcnt(0)
	v_addc_co_u32_e32 v37, vcc, 0, v207, vcc
	global_load_dwordx4 v[54:57], v[36:37], off offset:512
	global_load_dwordx4 v[46:49], v[34:35], off offset:16
	v_pk_mul_f32 v[64:65], v[74:75], s[54:55] op_sel_hi:[1,0]
	s_nop 0
	v_fma_f32 v34, -v64, v64, v65
	v_add_f32_e32 v34, 0x3727c5ac, v34
	v_rsq_f32_e32 v62, v34
	s_waitcnt vmcnt(6)
	v_sub_f32_e32 v35, v51, v64
	v_sub_f32_e32 v34, v50, v64
	v_sub_f32_e32 v37, v53, v64
	v_pk_mul_f32 v[34:35], v[62:63], v[34:35] op_sel_hi:[0,1]
	v_sub_f32_e32 v36, v52, v64
	v_pk_fma_f32 v[30:31], v[202:203], v[34:35], v[30:31]
	s_waitcnt vmcnt(5)
	v_sub_f32_e32 v35, v43, v64
	v_sub_f32_e32 v34, v42, v64
	v_pk_mul_f32 v[36:37], v[62:63], v[36:37] op_sel_hi:[0,1]
	v_pk_mul_f32 v[34:35], v[62:63], v[34:35] op_sel_hi:[0,1]
	v_pk_fma_f32 v[32:33], v[196:197], v[36:37], v[32:33]
	v_sub_f32_e32 v37, v45, v64
	v_sub_f32_e32 v36, v44, v64
	v_pk_fma_f32 v[26:27], v[194:195], v[34:35], v[26:27]
	v_pk_mul_f32 v[36:37], v[62:63], v[36:37] op_sel_hi:[0,1]
	v_pk_add_f32 v[38:39], v[190:191], v[26:27]
	v_add_co_u32_e32 v26, vcc, 0xa0000, v206
	v_pk_fma_f32 v[28:29], v[192:193], v[36:37], v[28:29]
	s_nop 0
	v_addc_co_u32_e32 v27, vcc, 0, v207, vcc
	v_pk_add_f32 v[32:33], v[198:199], v[32:33]
	v_pk_add_f32 v[30:31], v[200:201], v[30:31]
	v_pk_add_f32 v[40:41], v[188:189], v[28:29]
	s_and_b64 vcc, exec, s[42:43]
	global_store_dwordx4 v[60:61], v[30:33], off nt
	global_store_dwordx4 v[26:27], v[38:41], off offset:16 nt
	s_cbranch_vccnz .LBB0_1012
	v_add_co_u32_e32 v34, vcc, 0x50000, v204
	v_cvt_pk_bf16_f32 v26, v30, v31
	v_cvt_pk_bf16_f32 v27, v32, v33
	v_cvt_pk_bf16_f32 v28, v38, v39
	v_cvt_pk_bf16_f32 v29, v40, v41
	s_nop 1
	v_addc_co_u32_e32 v35, vcc, 0, v205, vcc
	global_store_dwordx4 v[34:35], v[26:29], off
.LBB0_1012:
	s_nop 1
	v_add_co_u32_e32 v26, vcc, 0xb0000, v206
	s_mov_b64 s[4:5], 0xb0000
	s_nop 0
	v_addc_co_u32_e32 v27, vcc, 0, v207, vcc
	v_lshl_add_u64 v[42:43], v[206:207], 0, s[4:5]
	global_load_dwordx4 v[34:37], v[26:27], off
	s_nop 0
	global_load_dwordx4 v[26:29], v[42:43], off offset:16
	v_mov_b32_e32 v63, v62
	s_waitcnt vmcnt(5)
	v_sub_f32_e32 v45, v55, v64
	v_sub_f32_e32 v44, v54, v64
	v_pk_mul_f32 v[44:45], v[62:63], v[44:45]
	v_sub_f32_e32 v51, v57, v64
	v_pk_fma_f32 v[22:23], v[210:211], v[44:45], v[22:23]
	s_waitcnt vmcnt(4)
	v_sub_f32_e32 v45, v47, v64
	v_sub_f32_e32 v44, v46, v64
	v_sub_f32_e32 v50, v56, v64
	v_mov_b32_e32 v52, v62
	v_mov_b32_e32 v53, v62
	v_sub_f32_e32 v47, v49, v64
	v_sub_f32_e32 v46, v48, v64
	v_pk_mul_f32 v[44:45], v[62:63], v[44:45]
	v_pk_mul_f32 v[50:51], v[52:53], v[50:51]
	v_pk_mul_f32 v[46:47], v[52:53], v[46:47]
	v_pk_fma_f32 v[18:19], v[144:145], v[44:45], v[18:19]
	v_add_co_u32_e32 v44, vcc, 0xa0000, v206
	v_pk_fma_f32 v[24:25], v[208:209], v[50:51], v[24:25]
	v_pk_fma_f32 v[20:21], v[142:143], v[46:47], v[20:21]
	v_addc_co_u32_e32 v45, vcc, 0, v207, vcc
	v_pk_add_f32 v[24:25], v[146:147], v[24:25]
	v_pk_add_f32 v[22:23], v[148:149], v[22:23]
	v_pk_add_f32 v[20:21], v[140:141], v[20:21]
	v_pk_add_f32 v[18:19], v[138:139], v[18:19]
	s_and_b64 vcc, exec, s[42:43]
	global_store_dwordx4 v[44:45], v[22:25], off offset:512 nt
	global_store_dwordx4 v[44:45], v[18:21], off offset:528 nt
	s_cbranch_vccnz .LBB0_1014
	v_add_co_u32_e32 v48, vcc, 0x50000, v204
	v_cvt_pk_bf16_f32 v44, v22, v23
	v_cvt_pk_bf16_f32 v45, v24, v25
	v_cvt_pk_bf16_f32 v46, v18, v19
	v_cvt_pk_bf16_f32 v47, v20, v21
	s_nop 1
	v_addc_co_u32_e32 v49, vcc, 0, v205, vcc
	global_store_dwordx4 v[48:49], v[44:47], off offset:256

; __device__ __forceinline__ unsigned cvt_pk_bf16(float lo, float hi) { unsigned r; asm volatile("v_cvt_pk_bf16_f32 %0, %1, %2" : "=v"(r) : "v"(lo), "v"(hi)); return r; }
; __device__ __forceinline__ void stats_mr(const f32x2 s, float& mu, float& r) { mu = s.x * (1.0f / 1024.0f); const float var = s.y * (1.0f / 1024.0f) - mu * mu; r = __builtin_amdgcn_rsqf(var + 1e-5f); }
;     __device__ __forceinline__ void operator()(const f32x4 (&acc)[2][2][4][2], const Unit& u, int wr, int wc, int fr, int fq) const {
;     ...
;         for (int g = 0; g < 8; ++g) { const int ai = g >> 2, m = g & 3; const int rr = ai * HALF + m * 16, rn = ((g + 1) >> 2) * HALF + ((g + 1) & 3) * 16;
;             f32x2 sv_n = sv_c; if (g + 1 < 8) sv_n = *(const f32x2*)(sp + (size_t)rn * 8 + ls);
;             float mu, r; stats_mr(sv_c, mu, r); float s1 = 0.f, s2 = 0.f;
; #pragma unroll
;             for (int bj = 0; bj < 2; ++bj) { const size_t ro = (size_t)rr * ldc + bj * HALF;
;                 f32x4 q0 = p0, q1 = p1;
;                 if (bj == 0) { q0 = *(const f32x4*)(bp + (ro + HALF) * 4 + l4); q1 = *(const f32x4*)(bp + (ro + HALF) * 4 + l4 + 16); }
;                 else if (g + 1 < 8) { q0 = *(const f32x4*)(bp + (size_t)rn * ldc * 4 + l4); q1 = *(const f32x4*)(bp + (size_t)rn * ldc * 4 + l4 + 16); }
;                 const f32x4 z0 = gv[bj][0] * ((p0 - mu) * r) + acc[ai][bj][m][0] + cv[bj][0], z1 = gv[bj][1] * ((p1 - mu) * r) + acc[ai][bj][m][1] + cv[bj][1];
;                 *(f32x4*)(op + ro * 4 + l4) = z0; *(f32x4*)(op + ro * 4 + l4 + 16) = z1;
;                 s1 += ((z0[0] + z0[1]) + (z0[2] + z0[3])) + ((z1[0] + z1[1]) + (z1[2] + z1[3]));
;                 s2 += ((z0[0] * z0[0] + z0[1] * z0[1]) + (z0[2] * z0[2] + z0[3] * z0[3])) + ((z1[0] * z1[0] + z1[1] * z1[1]) + (z1[2] * z1[2] + z1[3] * z1[3]));
;                 if (zb) { u32x4 w; w.x = cvt_pk_bf16(z0[0], z0[1]); w.y = cvt_pk_bf16(z0[2], z0[3]); w.z = cvt_pk_bf16(z1[0], z1[1]); w.w = cvt_pk_bf16(z1[2], z1[3]); *(u32x4*)(zp + ro * 2 + l2) = w; }
;                 p0 = q0; p1 = q1; }
.LBB0_1016:
	s_or_b64 exec, exec, s[24:25]
	s_mov_b64 s[4:5], 0xb0200
	v_lshl_add_u64 v[18:19], v[206:207], 0, s[4:5]
	s_mov_b32 s4, 0xb0000
	s_waitcnt lgkmcnt(1)
	v_add_co_u32_e32 v20, vcc, s4, v206
	v_pk_mul_f32 v[32:33], v[58:59], s[54:55] op_sel_hi:[1,0]
	s_waitcnt lgkmcnt(0)
	v_addc_co_u32_e32 v21, vcc, 0, v207, vcc
	global_load_dwordx4 v[22:25], v[20:21], off offset:512
	s_nop 0
	global_load_dwordx4 v[18:21], v[18:19], off offset:16
	v_fma_f32 v30, -v32, v32, v33
	v_add_f32_e32 v30, 0x3727c5ac, v30
	v_rsq_f32_e32 v30, v30
	s_waitcnt vmcnt(4)
	v_sub_f32_e32 v27, v27, v32
	v_sub_f32_e32 v26, v26, v32
	v_sub_f32_e32 v35, v35, v32
	v_sub_f32_e32 v34, v34, v32
	v_sub_f32_e32 v37, v37, v32
	v_sub_f32_e32 v36, v36, v32
	v_sub_f32_e32 v29, v29, v32
	v_sub_f32_e32 v28, v28, v32
	v_pk_mul_f32 v[26:27], v[30:31], v[26:27] op_sel_hi:[0,1]
	v_pk_mul_f32 v[36:37], v[30:31], v[36:37] op_sel_hi:[0,1]
	v_pk_mul_f32 v[34:35], v[30:31], v[34:35] op_sel_hi:[0,1]
	v_pk_mul_f32 v[28:29], v[30:31], v[28:29] op_sel_hi:[0,1]
	v_pk_fma_f32 v[10:11], v[194:195], v[26:27], v[10:11]
	v_add_co_u32_e32 v26, vcc, 0xb0000, v206
	v_pk_fma_f32 v[14:15], v[202:203], v[34:35], v[14:15]
	v_pk_fma_f32 v[16:17], v[196:197], v[36:37], v[16:17]
	v_pk_fma_f32 v[12:13], v[192:193], v[28:29], v[12:13]
	v_addc_co_u32_e32 v27, vcc, 0, v207, vcc
	v_pk_add_f32 v[16:17], v[198:199], v[16:17]
	v_pk_add_f32 v[14:15], v[200:201], v[14:15]
	v_pk_add_f32 v[12:13], v[188:189], v[12:13]
	v_pk_add_f32 v[10:11], v[190:191], v[10:11]
	s_and_b64 vcc, exec, s[42:43]
	global_store_dwordx4 v[42:43], v[14:17], off nt
	global_store_dwordx4 v[26:27], v[10:13], off offset:16 nt
	s_cbranch_vccnz .LBB0_1018
	v_add_co_u32_e32 v34, vcc, 0x58000, v204
	v_cvt_pk_bf16_f32 v26, v14, v15
	v_cvt_pk_bf16_f32 v27, v16, v17
	v_cvt_pk_bf16_f32 v28, v10, v11
	v_cvt_pk_bf16_f32 v29, v12, v13
	s_nop 1
	v_addc_co_u32_e32 v35, vcc, 0, v205, vcc
	global_store_dwordx4 v[34:35], v[26:29], off
.LBB0_1018:
	v_mov_b32_e32 v31, v30
	s_waitcnt vmcnt(2)
	v_sub_f32_e32 v19, v19, v32
	v_sub_f32_e32 v18, v18, v32
	v_sub_f32_e32 v23, v23, v32
	v_sub_f32_e32 v22, v22, v32
	v_sub_f32_e32 v25, v25, v32
	v_sub_f32_e32 v24, v24, v32
	v_mov_b32_e32 v26, v30
	v_mov_b32_e32 v27, v30
	v_sub_f32_e32 v21, v21, v32
	v_sub_f32_e32 v20, v20, v32
	v_pk_mul_f32 v[18:19], v[30:31], v[18:19]
	v_pk_mul_f32 v[24:25], v[26:27], v[24:25]
	v_pk_mul_f32 v[22:23], v[30:31], v[22:23]
	v_pk_mul_f32 v[20:21], v[26:27], v[20:21]
	v_pk_fma_f32 v[2:3], v[144:145], v[18:19], v[2:3]
	v_add_co_u32_e32 v18, vcc, 0xb0000, v206
	v_pk_fma_f32 v[6:7], v[210:211], v[22:23], v[6:7]
	v_pk_fma_f32 v[8:9], v[208:209], v[24:25], v[8:9]
	v_pk_fma_f32 v[4:5], v[142:143], v[20:21], v[4:5]
	v_addc_co_u32_e32 v19, vcc, 0, v207, vcc
	v_pk_add_f32 v[8:9], v[146:147], v[8:9]
	v_pk_add_f32 v[6:7], v[148:149], v[6:7]
	v_pk_add_f32 v[4:5], v[140:141], v[4:5]
	v_pk_add_f32 v[2:3], v[138:139], v[2:3]
	s_and_b64 vcc, exec, s[42:43]
	global_store_dwordx4 v[18:19], v[6:9], off offset:512 nt
	global_store_dwordx4 v[18:19], v[2:5], off offset:528 nt
	s_cbranch_vccnz .LBB0_1020
	v_add_co_u32_e32 v22, vcc, 0x58000, v204
	v_cvt_pk_bf16_f32 v18, v6, v7
	v_cvt_pk_bf16_f32 v19, v8, v9
	v_cvt_pk_bf16_f32 v20, v2, v3
	v_cvt_pk_bf16_f32 v21, v4, v5
	s_nop 1
	v_addc_co_u32_e32 v23, vcc, 0, v205, vcc
	global_store_dwordx4 v[22:23], v[18:21], off offset:256
